# GEMM K-loops: the barrier closing each 32-MFMA block moved 4 MFMAs earlier so the partner half starts while the block's tail still issues
# baseline (speedup 1.0000x reference)
; #define PG8_STAGE(bufoff, gbase, voff) do { _Pragma("unroll") for (int _i = 0; _i < 2; ++_i) \
;         __builtin_amdgcn_global_load_lds((const unsigned*)((const char*)(gbase) + (voff)[_i]), (PG8_LAS unsigned*)(lds + (bufoff) + ldsw + _i * 8192), 16, 0, 0); } while (0)
; #define PG8_STAGEA(bufoff, gbase, voff) do { _Pragma("unroll") for (int _i = 0; _i < 2; ++_i) \
;         __builtin_amdgcn_global_load_lds((const unsigned*)((const char*)(gbase) + (voff)[_i]), (PG8_LAS unsigned*)(lds + (bufoff) + ldsw + _i * 8192), 16, 0, A_AUX); } while (0)
; #define PG8_LDA(dst, b, h) do { _Pragma("unroll") for (int m = 0; m < 4; ++m) _Pragma("unroll") for (int k = 0; k < 2; ++k) dst[m][k] = *(const PG8_LAS bf16x8*)(lds + PG8_SA(b, h) + aoff + m * 2048 + k * 1024); } while (0)
; #define PG8_WAIT_V(n) asm volatile("s_waitcnt vmcnt(" #n ")" ::: "memory")
; #define PG8_BAR __builtin_amdgcn_s_barrier()
;     ...
;         for (int t = 0; t < nt; t += 2) {
;             const bool last = (t == nt - 2);
;             const char* a1 = cA + (size_t)(t + 1) * kstep;
;             const char* a2 = last ? nA : cA + (size_t)(t + 2) * kstep; const char* b2 = last ? nB : cB + (size_t)(t + 2) * kstep;
;             const char* a3 = a2 + kstep; const char* b3 = b2 + kstep;
;             if (last && has_next) S.a_ready(nxt);
;             if constexpr (SP2) {
;             PG8_LDB(B0, 0, 0); PG8_LDB(B1, 0, 1); PG8_SCHED; PG8_LDA(At, 0, 0); PG8_STAGEA(PG8_SA(1, 1), a1 + hstep, voffA);
;             PG8_WAIT_V(8); PG8_WAIT_L(0); PG8_BAR; PG8_MMA(0, 0, At, B0); PG8_MMA(0, 1, At, B1); PG8_BAR; PG8_SCHED;
;             PG8_LDA(At, 0, 1); PG8_STAGE(PG8_SB(0, 0), b2, voffB); PG8_STAGE(PG8_SB(0, 1), b2 + hstep, voffB); PG8_STAGEA(PG8_SA(0, 0), a2, voffA);
;             PG8_WAIT_V(8); PG8_WAIT_L(0); PG8_BAR; PG8_MMA(1, 0, At, B0); PG8_MMA(1, 1, At, B1); PG8_BAR; PG8_SCHED;
;             PG8_LDB(B0, 1, 0); PG8_LDB(B1, 1, 1); PG8_SCHED; PG8_LDA(At, 1, 0); PG8_STAGEA(PG8_SA(0, 1), a2 + hstep, voffA);
;             PG8_WAIT_V(8); PG8_WAIT_L(0); PG8_BAR; PG8_MMA(0, 0, At, B0); PG8_MMA(0, 1, At, B1); PG8_BAR; PG8_SCHED;
;             PG8_LDA(At, 1, 1); PG8_STAGE(PG8_SB(1, 0), b3, voffB); PG8_STAGE(PG8_SB(1, 1), b3 + hstep, voffB); PG8_STAGEA(PG8_SA(1, 0), a3, voffA);
;             PG8_WAIT_V(8); PG8_WAIT_L(0); PG8_BAR; PG8_MMA(1, 0, At, B0); PG8_MMA(1, 1, At, B1); PG8_BAR; PG8_SCHED;
.LBB0_186:
	s_add_u32 s40, s0, 0xfffc0080
	s_addc_u32 s41, s1, -1
	s_add_i32 s70, 0, 0x10000
	s_cmp_eq_u32 vcc_lo, 12
	s_cselect_b32 s43, s16, s41
	s_cselect_b32 s42, s17, s40
	s_cselect_b32 s41, s51, s59
	s_cselect_b32 s40, s53, s58
	s_add_i32 vcc_hi, 0, 0x14000
	v_add_u32_e32 v94, s70, v201
	v_add_u32_e32 v158, vcc_hi, v201
	ds_read_b128 v[74:77], v94
	ds_read_b128 v[78:81], v94 offset:1024
	ds_read_b128 v[90:93], v94 offset:2048
	ds_read_b128 v[94:97], v94 offset:3072
	ds_read_b128 v[146:149], v158
	ds_read_b128 v[150:153], v158 offset:1024
	ds_read_b128 v[154:157], v158 offset:2048
	ds_read_b128 v[158:161], v158 offset:3072
	v_lshl_add_u64 v[190:191], s[0:1], 0, v[182:183]
	s_add_i32 m0, s61, 0xc000
	ds_read_b128 v[186:189], v203
	ds_read_b128 v[208:211], v203 offset:1024
	ds_read_b128 v[212:215], v203 offset:2048
	ds_read_b128 v[216:219], v203 offset:3072
	ds_read_b128 v[220:223], v203 offset:4096
	ds_read_b128 v[224:227], v203 offset:5120
	ds_read_b128 v[228:231], v203 offset:6144
	ds_read_b128 v[232:235], v203 offset:7168
	global_load_lds_dwordx4 v[190:191], off
	v_lshl_add_u64 v[190:191], s[0:1], 0, v[184:185]
	s_add_i32 m0, s61, 0xe000
	s_nop 0
	global_load_lds_dwordx4 v[190:191], off
	s_waitcnt vmcnt(8)
	s_waitcnt lgkmcnt(0)
	s_barrier
	s_setprio 1
	s_waitcnt lgkmcnt(0)
	v_mfma_f32_16x16x32_bf16 v[142:145], v[74:77], v[186:189], v[142:145]
	v_mfma_f32_16x16x32_bf16 v[138:141], v[90:93], v[186:189], v[138:141]
	v_mfma_f32_16x16x32_bf16 v[126:129], v[74:77], v[212:215], v[126:129]
	v_mfma_f32_16x16x32_bf16 v[122:125], v[90:93], v[212:215], v[122:125]
	v_mfma_f32_16x16x32_bf16 v[110:113], v[74:77], v[220:223], v[110:113]
	v_mfma_f32_16x16x32_bf16 v[106:109], v[90:93], v[220:223], v[106:109]
	v_mfma_f32_16x16x32_bf16 v[86:89], v[74:77], v[228:231], v[86:89]
	v_mfma_f32_16x16x32_bf16 v[82:85], v[90:93], v[228:231], v[82:85]
	v_mfma_f32_16x16x32_bf16 v[142:145], v[78:81], v[208:211], v[142:145]
	v_mfma_f32_16x16x32_bf16 v[138:141], v[94:97], v[208:211], v[138:141]
	v_mfma_f32_16x16x32_bf16 v[126:129], v[78:81], v[216:219], v[126:129]
	v_mfma_f32_16x16x32_bf16 v[122:125], v[94:97], v[216:219], v[122:125]
	v_mfma_f32_16x16x32_bf16 v[110:113], v[78:81], v[224:227], v[110:113]
	v_mfma_f32_16x16x32_bf16 v[106:109], v[94:97], v[224:227], v[106:109]
	v_mfma_f32_16x16x32_bf16 v[86:89], v[78:81], v[232:235], v[86:89]
	v_mfma_f32_16x16x32_bf16 v[82:85], v[94:97], v[232:235], v[82:85]
	s_setprio 0
	s_setprio 1
	v_mfma_f32_16x16x32_bf16 v[134:137], v[146:149], v[186:189], v[134:137]
	v_mfma_f32_16x16x32_bf16 v[130:133], v[154:157], v[186:189], v[130:133]
	v_mfma_f32_16x16x32_bf16 v[118:121], v[146:149], v[212:215], v[118:121]
	v_mfma_f32_16x16x32_bf16 v[114:117], v[154:157], v[212:215], v[114:117]
	v_mfma_f32_16x16x32_bf16 v[102:105], v[146:149], v[220:223], v[102:105]
	v_mfma_f32_16x16x32_bf16 v[98:101], v[154:157], v[220:223], v[98:101]
	v_mfma_f32_16x16x32_bf16 v[70:73], v[146:149], v[228:231], v[70:73]
	v_mfma_f32_16x16x32_bf16 v[66:69], v[154:157], v[228:231], v[66:69]
	v_mfma_f32_16x16x32_bf16 v[134:137], v[150:153], v[208:211], v[134:137]
	v_mfma_f32_16x16x32_bf16 v[130:133], v[158:161], v[208:211], v[130:133]
	v_mfma_f32_16x16x32_bf16 v[118:121], v[150:153], v[216:219], v[118:121]
	v_mfma_f32_16x16x32_bf16 v[114:117], v[158:161], v[216:219], v[114:117]
	s_barrier
	v_mfma_f32_16x16x32_bf16 v[102:105], v[150:153], v[224:227], v[102:105]
	v_mfma_f32_16x16x32_bf16 v[98:101], v[158:161], v[224:227], v[98:101]
	v_mfma_f32_16x16x32_bf16 v[70:73], v[150:153], v[232:235], v[70:73]
	v_mfma_f32_16x16x32_bf16 v[66:69], v[158:161], v[232:235], v[66:69]
	s_setprio 0
	s_nop 0
	s_add_i32 s70, s70, s60
	v_lshl_add_u64 v[190:191], s[40:41], 0, v[0:1]
	s_mov_b32 m0, s70
	ds_read_b128 v[186:189], v203 offset:16384
	ds_read_b128 v[208:211], v203 offset:17408
	ds_read_b128 v[212:215], v203 offset:18432
	ds_read_b128 v[216:219], v203 offset:19456
	ds_read_b128 v[220:223], v203 offset:20480
	ds_read_b128 v[224:227], v203 offset:21504
	ds_read_b128 v[228:231], v203 offset:22528
	ds_read_b128 v[232:235], v203 offset:23552
	global_load_lds_dwordx4 v[190:191], off
	s_add_i32 m0, s70, 0x2000
	s_add_u32 s70, s40, 0x40000
	v_lshl_add_u64 v[236:237], s[40:41], 0, v[174:175]
	s_addc_u32 s71, s41, 0
	s_add_i32 vcc_hi, vcc_hi, s60
	global_load_lds_dwordx4 v[236:237], off
	v_lshl_add_u64 v[238:239], s[70:71], 0, v[0:1]
	s_mov_b32 m0, vcc_hi
	v_lshl_add_u64 v[240:241], s[42:43], 0, v[176:177]
	global_load_lds_dwordx4 v[238:239], off
	v_lshl_add_u64 v[238:239], s[70:71], 0, v[174:175]
	s_add_i32 m0, vcc_hi, 0x2000
	s_nop 0
	global_load_lds_dwordx4 v[238:239], off
	v_lshl_add_u64 v[238:239], s[42:43], 0, v[178:179]
	s_mov_b32 m0, s61
	s_nop 0
	global_load_lds_dwordx4 v[238:239], off
	s_mov_b32 m0, s62
	s_nop 0
	global_load_lds_dwordx4 v[240:241], off
	s_waitcnt vmcnt(8)
	s_waitcnt lgkmcnt(0)
	s_barrier
; #define PG8_STAGE(bufoff, gbase, voff) do { _Pragma("unroll") for (int _i = 0; _i < 2; ++_i) \
;         __builtin_amdgcn_global_load_lds((const unsigned*)((const char*)(gbase) + (voff)[_i]), (PG8_LAS unsigned*)(lds + (bufoff) + ldsw + _i * 8192), 16, 0, 0); } while (0)
; #define PG8_STAGEA(bufoff, gbase, voff) do { _Pragma("unroll") for (int _i = 0; _i < 2; ++_i) \
;         __builtin_amdgcn_global_load_lds((const unsigned*)((const char*)(gbase) + (voff)[_i]), (PG8_LAS unsigned*)(lds + (bufoff) + ldsw + _i * 8192), 16, 0, A_AUX); } while (0)
; #define PG8_LDA(dst, b, h) do { _Pragma("unroll") for (int m = 0; m < 4; ++m) _Pragma("unroll") for (int k = 0; k < 2; ++k) dst[m][k] = *(const PG8_LAS bf16x8*)(lds + PG8_SA(b, h) + aoff + m * 2048 + k * 1024); } while (0)
; #define PG8_WAIT_V(n) asm volatile("s_waitcnt vmcnt(" #n ")" ::: "memory")
; #define PG8_BAR __builtin_amdgcn_s_barrier()
;     ...
;         for (int t = 0; t < nt; t += 2) {
;             const bool last = (t == nt - 2);
;             const char* a1 = cA + (size_t)(t + 1) * kstep;
;             const char* a2 = last ? nA : cA + (size_t)(t + 2) * kstep; const char* b2 = last ? nB : cB + (size_t)(t + 2) * kstep;
;             const char* a3 = a2 + kstep; const char* b3 = b2 + kstep;
;             if (last && has_next) S.a_ready(nxt);
;             if constexpr (SP2) {
;             PG8_LDB(B0, 0, 0); PG8_LDB(B1, 0, 1); PG8_SCHED; PG8_LDA(At, 0, 0); PG8_STAGEA(PG8_SA(1, 1), a1 + hstep, voffA);
;             PG8_WAIT_V(8); PG8_WAIT_L(0); PG8_BAR; PG8_MMA(0, 0, At, B0); PG8_MMA(0, 1, At, B1); PG8_BAR; PG8_SCHED;
;             PG8_LDA(At, 0, 1); PG8_STAGE(PG8_SB(0, 0), b2, voffB); PG8_STAGE(PG8_SB(0, 1), b2 + hstep, voffB); PG8_STAGEA(PG8_SA(0, 0), a2, voffA);
;             PG8_WAIT_V(8); PG8_WAIT_L(0); PG8_BAR; PG8_MMA(1, 0, At, B0); PG8_MMA(1, 1, At, B1); PG8_BAR; PG8_SCHED;
;             PG8_LDB(B0, 1, 0); PG8_LDB(B1, 1, 1); PG8_SCHED; PG8_LDA(At, 1, 0); PG8_STAGEA(PG8_SA(0, 1), a2 + hstep, voffA);
;             PG8_WAIT_V(8); PG8_WAIT_L(0); PG8_BAR; PG8_MMA(0, 0, At, B0); PG8_MMA(0, 1, At, B1); PG8_BAR; PG8_SCHED;
;             PG8_LDA(At, 1, 1); PG8_STAGE(PG8_SB(1, 0), b3, voffB); PG8_STAGE(PG8_SB(1, 1), b3 + hstep, voffB); PG8_STAGEA(PG8_SA(1, 0), a3, voffA);
;             PG8_WAIT_V(8); PG8_WAIT_L(0); PG8_BAR; PG8_MMA(1, 0, At, B0); PG8_MMA(1, 1, At, B1); PG8_BAR; PG8_SCHED;
	s_setprio 1
	s_waitcnt lgkmcnt(0)
	v_mfma_f32_16x16x32_bf16 v[62:65], v[74:77], v[186:189], v[62:65]
	v_mfma_f32_16x16x32_bf16 v[58:61], v[90:93], v[186:189], v[58:61]
	v_mfma_f32_16x16x32_bf16 v[46:49], v[74:77], v[212:215], v[46:49]
	v_mfma_f32_16x16x32_bf16 v[42:45], v[90:93], v[212:215], v[42:45]
	v_mfma_f32_16x16x32_bf16 v[30:33], v[74:77], v[220:223], v[30:33]
	v_mfma_f32_16x16x32_bf16 v[26:29], v[90:93], v[220:223], v[26:29]
	v_mfma_f32_16x16x32_bf16 v[14:17], v[74:77], v[228:231], v[14:17]
	v_mfma_f32_16x16x32_bf16 v[10:13], v[90:93], v[228:231], v[10:13]
	v_mfma_f32_16x16x32_bf16 v[62:65], v[78:81], v[208:211], v[62:65]
	v_mfma_f32_16x16x32_bf16 v[58:61], v[94:97], v[208:211], v[58:61]
	v_mfma_f32_16x16x32_bf16 v[46:49], v[78:81], v[216:219], v[46:49]
	v_mfma_f32_16x16x32_bf16 v[42:45], v[94:97], v[216:219], v[42:45]
	v_mfma_f32_16x16x32_bf16 v[30:33], v[78:81], v[224:227], v[30:33]
	v_mfma_f32_16x16x32_bf16 v[26:29], v[94:97], v[224:227], v[26:29]
	v_mfma_f32_16x16x32_bf16 v[14:17], v[78:81], v[232:235], v[14:17]
	v_mfma_f32_16x16x32_bf16 v[10:13], v[94:97], v[232:235], v[10:13]
	s_setprio 0
	s_setprio 1
	v_mfma_f32_16x16x32_bf16 v[54:57], v[146:149], v[186:189], v[54:57]
	v_mfma_f32_16x16x32_bf16 v[50:53], v[154:157], v[186:189], v[50:53]
	v_mfma_f32_16x16x32_bf16 v[38:41], v[146:149], v[212:215], v[38:41]
	v_mfma_f32_16x16x32_bf16 v[34:37], v[154:157], v[212:215], v[34:37]
	v_mfma_f32_16x16x32_bf16 v[22:25], v[146:149], v[220:223], v[22:25]
	v_mfma_f32_16x16x32_bf16 v[18:21], v[154:157], v[220:223], v[18:21]
	v_mfma_f32_16x16x32_bf16 v[6:9], v[146:149], v[228:231], v[6:9]
	v_mfma_f32_16x16x32_bf16 v[2:5], v[154:157], v[228:231], v[2:5]
	v_mfma_f32_16x16x32_bf16 v[54:57], v[150:153], v[208:211], v[54:57]
	v_mfma_f32_16x16x32_bf16 v[50:53], v[158:161], v[208:211], v[50:53]
	v_mfma_f32_16x16x32_bf16 v[38:41], v[150:153], v[216:219], v[38:41]
	v_mfma_f32_16x16x32_bf16 v[34:37], v[158:161], v[216:219], v[34:37]
	s_barrier
	v_mfma_f32_16x16x32_bf16 v[22:25], v[150:153], v[224:227], v[22:25]
	v_mfma_f32_16x16x32_bf16 v[18:21], v[158:161], v[224:227], v[18:21]
	v_mfma_f32_16x16x32_bf16 v[6:9], v[150:153], v[232:235], v[6:9]
	v_mfma_f32_16x16x32_bf16 v[2:5], v[158:161], v[232:235], v[2:5]
	s_setprio 0
	s_nop 0
	s_add_i32 s70, 0, 0x18000
	s_add_i32 s71, 0, 0x1c000
	v_add_u32_e32 v94, s70, v201
	v_add_u32_e32 v158, s71, v201
	ds_read_b128 v[74:77], v94
	ds_read_b128 v[78:81], v94 offset:1024
	ds_read_b128 v[90:93], v94 offset:2048
	ds_read_b128 v[94:97], v94 offset:3072
	ds_read_b128 v[146:149], v158
	ds_read_b128 v[150:153], v158 offset:1024
	ds_read_b128 v[154:157], v158 offset:2048
	ds_read_b128 v[158:161], v158 offset:3072
	s_add_u32 s42, s42, 0x40000
	s_addc_u32 s43, s43, 0
	s_mov_b32 m0, s63
	v_lshl_add_u64 v[242:243], s[42:43], 0, v[178:179]
	ds_read_b128 v[186:189], v203 offset:32768
	ds_read_b128 v[208:211], v203 offset:33792
	ds_read_b128 v[212:215], v203 offset:34816
	ds_read_b128 v[216:219], v203 offset:35840
	ds_read_b128 v[220:223], v203 offset:36864
	ds_read_b128 v[224:227], v203 offset:37888
	ds_read_b128 v[228:231], v203 offset:38912
	ds_read_b128 v[232:235], v203 offset:39936
	global_load_lds_dwordx4 v[242:243], off
	v_lshl_add_u64 v[242:243], s[42:43], 0, v[176:177]
	s_mov_b32 m0, s64
	s_nop 0
	global_load_lds_dwordx4 v[242:243], off
	s_waitcnt vmcnt(8)
	s_waitcnt lgkmcnt(0)
	s_barrier
	s_setprio 1
	s_waitcnt lgkmcnt(0)
	v_mfma_f32_16x16x32_bf16 v[142:145], v[74:77], v[186:189], v[142:145]
	v_mfma_f32_16x16x32_bf16 v[138:141], v[90:93], v[186:189], v[138:141]
	v_mfma_f32_16x16x32_bf16 v[126:129], v[74:77], v[212:215], v[126:129]
	v_mfma_f32_16x16x32_bf16 v[122:125], v[90:93], v[212:215], v[122:125]
	v_mfma_f32_16x16x32_bf16 v[110:113], v[74:77], v[220:223], v[110:113]
	v_mfma_f32_16x16x32_bf16 v[106:109], v[90:93], v[220:223], v[106:109]
	v_mfma_f32_16x16x32_bf16 v[86:89], v[74:77], v[228:231], v[86:89]
	v_mfma_f32_16x16x32_bf16 v[82:85], v[90:93], v[228:231], v[82:85]
	v_mfma_f32_16x16x32_bf16 v[142:145], v[78:81], v[208:211], v[142:145]
	v_mfma_f32_16x16x32_bf16 v[138:141], v[94:97], v[208:211], v[138:141]
	v_mfma_f32_16x16x32_bf16 v[126:129], v[78:81], v[216:219], v[126:129]
	v_mfma_f32_16x16x32_bf16 v[122:125], v[94:97], v[216:219], v[122:125]
	v_mfma_f32_16x16x32_bf16 v[110:113], v[78:81], v[224:227], v[110:113]
	v_mfma_f32_16x16x32_bf16 v[106:109], v[94:97], v[224:227], v[106:109]
	v_mfma_f32_16x16x32_bf16 v[86:89], v[78:81], v[232:235], v[86:89]
	v_mfma_f32_16x16x32_bf16 v[82:85], v[94:97], v[232:235], v[82:85]
	s_setprio 0
	s_setprio 1
	v_mfma_f32_16x16x32_bf16 v[134:137], v[146:149], v[186:189], v[134:137]
	v_mfma_f32_16x16x32_bf16 v[130:133], v[154:157], v[186:189], v[130:133]
	v_mfma_f32_16x16x32_bf16 v[118:121], v[146:149], v[212:215], v[118:121]
	v_mfma_f32_16x16x32_bf16 v[114:117], v[154:157], v[212:215], v[114:117]
	v_mfma_f32_16x16x32_bf16 v[102:105], v[146:149], v[220:223], v[102:105]
	v_mfma_f32_16x16x32_bf16 v[98:101], v[154:157], v[220:223], v[98:101]
	v_mfma_f32_16x16x32_bf16 v[70:73], v[146:149], v[228:231], v[70:73]
	v_mfma_f32_16x16x32_bf16 v[66:69], v[154:157], v[228:231], v[66:69]
	v_mfma_f32_16x16x32_bf16 v[134:137], v[150:153], v[208:211], v[134:137]
	v_mfma_f32_16x16x32_bf16 v[130:133], v[158:161], v[208:211], v[130:133]
	v_mfma_f32_16x16x32_bf16 v[118:121], v[150:153], v[216:219], v[118:121]
	v_mfma_f32_16x16x32_bf16 v[114:117], v[158:161], v[216:219], v[114:117]
	s_barrier
; #define PG8_STAGE(bufoff, gbase, voff) do { _Pragma("unroll") for (int _i = 0; _i < 2; ++_i) \
;         __builtin_amdgcn_global_load_lds((const unsigned*)((const char*)(gbase) + (voff)[_i]), (PG8_LAS unsigned*)(lds + (bufoff) + ldsw + _i * 8192), 16, 0, 0); } while (0)
; #define PG8_STAGEA(bufoff, gbase, voff) do { _Pragma("unroll") for (int _i = 0; _i < 2; ++_i) \
;         __builtin_amdgcn_global_load_lds((const unsigned*)((const char*)(gbase) + (voff)[_i]), (PG8_LAS unsigned*)(lds + (bufoff) + ldsw + _i * 8192), 16, 0, A_AUX); } while (0)
; #define PG8_LDA(dst, b, h) do { _Pragma("unroll") for (int m = 0; m < 4; ++m) _Pragma("unroll") for (int k = 0; k < 2; ++k) dst[m][k] = *(const PG8_LAS bf16x8*)(lds + PG8_SA(b, h) + aoff + m * 2048 + k * 1024); } while (0)
; #define PG8_WAIT_V(n) asm volatile("s_waitcnt vmcnt(" #n ")" ::: "memory")
; #define PG8_BAR __builtin_amdgcn_s_barrier()
;     ...
;         for (int t = 0; t < nt; t += 2) {
;             const bool last = (t == nt - 2);
;             const char* a1 = cA + (size_t)(t + 1) * kstep;
;             const char* a2 = last ? nA : cA + (size_t)(t + 2) * kstep; const char* b2 = last ? nB : cB + (size_t)(t + 2) * kstep;
;             const char* a3 = a2 + kstep; const char* b3 = b2 + kstep;
;             if (last && has_next) S.a_ready(nxt);
;             if constexpr (SP2) {
;             PG8_LDB(B0, 0, 0); PG8_LDB(B1, 0, 1); PG8_SCHED; PG8_LDA(At, 0, 0); PG8_STAGEA(PG8_SA(1, 1), a1 + hstep, voffA);
;             PG8_WAIT_V(8); PG8_WAIT_L(0); PG8_BAR; PG8_MMA(0, 0, At, B0); PG8_MMA(0, 1, At, B1); PG8_BAR; PG8_SCHED;
;             PG8_LDA(At, 0, 1); PG8_STAGE(PG8_SB(0, 0), b2, voffB); PG8_STAGE(PG8_SB(0, 1), b2 + hstep, voffB); PG8_STAGEA(PG8_SA(0, 0), a2, voffA);
;             PG8_WAIT_V(8); PG8_WAIT_L(0); PG8_BAR; PG8_MMA(1, 0, At, B0); PG8_MMA(1, 1, At, B1); PG8_BAR; PG8_SCHED;
;             PG8_LDB(B0, 1, 0); PG8_LDB(B1, 1, 1); PG8_SCHED; PG8_LDA(At, 1, 0); PG8_STAGEA(PG8_SA(0, 1), a2 + hstep, voffA);
;             PG8_WAIT_V(8); PG8_WAIT_L(0); PG8_BAR; PG8_MMA(0, 0, At, B0); PG8_MMA(0, 1, At, B1); PG8_BAR; PG8_SCHED;
;             PG8_LDA(At, 1, 1); PG8_STAGE(PG8_SB(1, 0), b3, voffB); PG8_STAGE(PG8_SB(1, 1), b3 + hstep, voffB); PG8_STAGEA(PG8_SA(1, 0), a3, voffA);
;             PG8_WAIT_V(8); PG8_WAIT_L(0); PG8_BAR; PG8_MMA(1, 0, At, B0); PG8_MMA(1, 1, At, B1); PG8_BAR; PG8_SCHED;
	v_mfma_f32_16x16x32_bf16 v[102:105], v[150:153], v[224:227], v[102:105]
	v_mfma_f32_16x16x32_bf16 v[98:101], v[158:161], v[224:227], v[98:101]
	v_mfma_f32_16x16x32_bf16 v[70:73], v[150:153], v[232:235], v[70:73]
	v_mfma_f32_16x16x32_bf16 v[66:69], v[158:161], v[232:235], v[66:69]
	s_setprio 0
	s_nop 0
	s_add_i32 s42, s70, s60
	v_lshl_add_u64 v[190:191], v[190:191], 0, s[8:9]
	s_mov_b32 m0, s42
	ds_read_b128 v[186:189], v203 offset:49152
	ds_read_b128 v[208:211], v203 offset:50176
	ds_read_b128 v[212:215], v203 offset:51200
	ds_read_b128 v[216:219], v203 offset:52224
	ds_read_b128 v[220:223], v203 offset:53248
	ds_read_b128 v[224:227], v203 offset:54272
	ds_read_b128 v[228:231], v203 offset:55296
	ds_read_b128 v[232:235], v203 offset:56320
	global_load_lds_dwordx4 v[190:191], off
	s_add_i32 m0, s42, 0x2000
	s_add_u32 s40, s40, 0x40080
	v_lshl_add_u64 v[190:191], v[236:237], 0, s[8:9]
	s_addc_u32 s41, s41, 0
	s_add_i32 s42, s71, s60
	global_load_lds_dwordx4 v[190:191], off
	v_lshl_add_u64 v[190:191], s[40:41], 0, v[0:1]
	s_mov_b32 m0, s42
	s_nop 0
	global_load_lds_dwordx4 v[190:191], off
	v_lshl_add_u64 v[190:191], s[40:41], 0, v[174:175]
	s_add_i32 m0, s42, 0x2000
	s_nop 0
	global_load_lds_dwordx4 v[190:191], off
	v_lshl_add_u64 v[190:191], v[238:239], 0, s[8:9]
	s_mov_b32 m0, s72
	s_nop 0
	global_load_lds_dwordx4 v[190:191], off
	v_lshl_add_u64 v[190:191], v[240:241], 0, s[8:9]
	s_mov_b32 m0, s73
	s_nop 0
	global_load_lds_dwordx4 v[190:191], off
	s_waitcnt vmcnt(8)
	s_waitcnt lgkmcnt(0)
	s_barrier
	s_setprio 1
	s_waitcnt lgkmcnt(0)
	v_mfma_f32_16x16x32_bf16 v[62:65], v[74:77], v[186:189], v[62:65]
	v_mfma_f32_16x16x32_bf16 v[58:61], v[90:93], v[186:189], v[58:61]
	v_mfma_f32_16x16x32_bf16 v[46:49], v[74:77], v[212:215], v[46:49]
	v_mfma_f32_16x16x32_bf16 v[42:45], v[90:93], v[212:215], v[42:45]
	v_mfma_f32_16x16x32_bf16 v[30:33], v[74:77], v[220:223], v[30:33]
	v_mfma_f32_16x16x32_bf16 v[26:29], v[90:93], v[220:223], v[26:29]
	v_mfma_f32_16x16x32_bf16 v[14:17], v[74:77], v[228:231], v[14:17]
	v_mfma_f32_16x16x32_bf16 v[10:13], v[90:93], v[228:231], v[10:13]
	v_mfma_f32_16x16x32_bf16 v[62:65], v[78:81], v[208:211], v[62:65]
	v_mfma_f32_16x16x32_bf16 v[58:61], v[94:97], v[208:211], v[58:61]
	v_mfma_f32_16x16x32_bf16 v[46:49], v[78:81], v[216:219], v[46:49]
	v_mfma_f32_16x16x32_bf16 v[42:45], v[94:97], v[216:219], v[42:45]
	v_mfma_f32_16x16x32_bf16 v[30:33], v[78:81], v[224:227], v[30:33]
	v_mfma_f32_16x16x32_bf16 v[26:29], v[94:97], v[224:227], v[26:29]
	v_mfma_f32_16x16x32_bf16 v[14:17], v[78:81], v[232:235], v[14:17]
	v_mfma_f32_16x16x32_bf16 v[10:13], v[94:97], v[232:235], v[10:13]
	s_setprio 0
	s_setprio 1
	v_mfma_f32_16x16x32_bf16 v[54:57], v[146:149], v[186:189], v[54:57]
	v_mfma_f32_16x16x32_bf16 v[50:53], v[154:157], v[186:189], v[50:53]
	v_mfma_f32_16x16x32_bf16 v[38:41], v[146:149], v[212:215], v[38:41]
	v_mfma_f32_16x16x32_bf16 v[34:37], v[154:157], v[212:215], v[34:37]
	v_mfma_f32_16x16x32_bf16 v[22:25], v[146:149], v[220:223], v[22:25]
	v_mfma_f32_16x16x32_bf16 v[18:21], v[154:157], v[220:223], v[18:21]
	v_mfma_f32_16x16x32_bf16 v[6:9], v[146:149], v[228:231], v[6:9]
	v_mfma_f32_16x16x32_bf16 v[2:5], v[154:157], v[228:231], v[2:5]
	v_mfma_f32_16x16x32_bf16 v[54:57], v[150:153], v[208:211], v[54:57]
	v_mfma_f32_16x16x32_bf16 v[50:53], v[158:161], v[208:211], v[50:53]
	v_mfma_f32_16x16x32_bf16 v[38:41], v[150:153], v[216:219], v[38:41]
	v_mfma_f32_16x16x32_bf16 v[34:37], v[158:161], v[216:219], v[34:37]
	s_barrier
	v_mfma_f32_16x16x32_bf16 v[22:25], v[150:153], v[224:227], v[22:25]
	v_mfma_f32_16x16x32_bf16 v[18:21], v[158:161], v[224:227], v[18:21]
	v_mfma_f32_16x16x32_bf16 v[6:9], v[150:153], v[232:235], v[6:9]
	v_mfma_f32_16x16x32_bf16 v[2:5], v[158:161], v[232:235], v[2:5]
	s_setprio 0
	s_nop 0
	s_add_i32 vcc_lo, vcc_lo, 2
	s_add_u32 s0, s0, 0x100
	s_addc_u32 s1, s1, 0
	s_add_u32 s58, s58, 0x100
	s_addc_u32 s59, s59, 0
	s_cmp_gt_u32 vcc_lo, 13
	s_cbranch_scc0 .LBB0_186
	s_and_b64 vcc, exec, s[46:47]
	s_cbranch_vccz .LBB0_189
	s_barrier

; #define PG8_STAGE(bufoff, gbase, voff) do { _Pragma("unroll") for (int _i = 0; _i < 2; ++_i) \
;         __builtin_amdgcn_global_load_lds((const unsigned*)((const char*)(gbase) + (voff)[_i]), (PG8_LAS unsigned*)(lds + (bufoff) + ldsw + _i * 8192), 16, 0, 0); } while (0)
; #define PG8_STAGEA(bufoff, gbase, voff) do { _Pragma("unroll") for (int _i = 0; _i < 2; ++_i) \
;         __builtin_amdgcn_global_load_lds((const unsigned*)((const char*)(gbase) + (voff)[_i]), (PG8_LAS unsigned*)(lds + (bufoff) + ldsw + _i * 8192), 16, 0, A_AUX); } while (0)
; #define PG8_LDA(dst, b, h) do { _Pragma("unroll") for (int m = 0; m < 4; ++m) _Pragma("unroll") for (int k = 0; k < 2; ++k) dst[m][k] = *(const PG8_LAS bf16x8*)(lds + PG8_SA(b, h) + aoff + m * 2048 + k * 1024); } while (0)
; #define PG8_WAIT_V(n) asm volatile("s_waitcnt vmcnt(" #n ")" ::: "memory")
; #define PG8_BAR __builtin_amdgcn_s_barrier()
;     ...
;         for (int t = 0; t < nt; t += 2) {
;             const bool last = (t == nt - 2);
;             const char* a1 = cA + (size_t)(t + 1) * kstep;
;             const char* a2 = last ? nA : cA + (size_t)(t + 2) * kstep; const char* b2 = last ? nB : cB + (size_t)(t + 2) * kstep;
;             const char* a3 = a2 + kstep; const char* b3 = b2 + kstep;
;             if (last && has_next) S.a_ready(nxt);
;             if constexpr (SP2) {
;             PG8_LDB(B0, 0, 0); PG8_LDB(B1, 0, 1); PG8_SCHED; PG8_LDA(At, 0, 0); PG8_STAGEA(PG8_SA(1, 1), a1 + hstep, voffA);
;             PG8_WAIT_V(8); PG8_WAIT_L(0); PG8_BAR; PG8_MMA(0, 0, At, B0); PG8_MMA(0, 1, At, B1); PG8_BAR; PG8_SCHED;
;             PG8_LDA(At, 0, 1); PG8_STAGE(PG8_SB(0, 0), b2, voffB); PG8_STAGE(PG8_SB(0, 1), b2 + hstep, voffB); PG8_STAGEA(PG8_SA(0, 0), a2, voffA);
;             PG8_WAIT_V(8); PG8_WAIT_L(0); PG8_BAR; PG8_MMA(1, 0, At, B0); PG8_MMA(1, 1, At, B1); PG8_BAR; PG8_SCHED;
;             PG8_LDB(B0, 1, 0); PG8_LDB(B1, 1, 1); PG8_SCHED; PG8_LDA(At, 1, 0); PG8_STAGEA(PG8_SA(0, 1), a2 + hstep, voffA);
;             PG8_WAIT_V(8); PG8_WAIT_L(0); PG8_BAR; PG8_MMA(0, 0, At, B0); PG8_MMA(0, 1, At, B1); PG8_BAR; PG8_SCHED;
;             PG8_LDA(At, 1, 1); PG8_STAGE(PG8_SB(1, 0), b3, voffB); PG8_STAGE(PG8_SB(1, 1), b3 + hstep, voffB); PG8_STAGEA(PG8_SA(1, 0), a3, voffA);
;             PG8_WAIT_V(8); PG8_WAIT_L(0); PG8_BAR; PG8_MMA(1, 0, At, B0); PG8_MMA(1, 1, At, B1); PG8_BAR; PG8_SCHED;
.LBB0_443:
	s_add_u32 s50, s48, 0xfffc0080
	s_addc_u32 s51, s49, -1
	s_add_i32 s70, 0, 0x10000
	s_cmp_eq_u32 s73, 12
	s_cselect_b32 s53, s16, s51
	s_cselect_b32 s52, s17, s50
	v_add_u32_e32 v140, s70, v143
	s_cselect_b32 s51, s41, s72
	s_cselect_b32 s50, s43, s65
	s_add_i32 s76, 0, 0x14000
	ds_read_b128 v[146:149], v140
	ds_read_b128 v[150:153], v140 offset:1024
	ds_read_b128 v[154:157], v140 offset:2048
	ds_read_b128 v[158:161], v140 offset:3072
	v_add_u32_e32 v140, s76, v143
	ds_read_b128 v[174:177], v140
	ds_read_b128 v[178:181], v140 offset:1024
	ds_read_b128 v[182:185], v140 offset:2048
	ds_read_b128 v[186:189], v140 offset:3072
	v_lshl_add_u64 v[140:141], s[48:49], 0, v[136:137]
	s_add_i32 m0, s56, 0xc000
	ds_read_b128 v[200:203], v145
	ds_read_b128 v[208:211], v145 offset:1024
	ds_read_b128 v[212:215], v145 offset:2048
	ds_read_b128 v[216:219], v145 offset:3072
	ds_read_b128 v[220:223], v145 offset:4096
	ds_read_b128 v[224:227], v145 offset:5120
	ds_read_b128 v[228:231], v145 offset:6144
	ds_read_b128 v[232:235], v145 offset:7168
	global_load_lds_dwordx4 v[140:141], off
	v_lshl_add_u64 v[140:141], s[48:49], 0, v[138:139]
	s_add_i32 m0, s56, 0xe000
	s_nop 0
	global_load_lds_dwordx4 v[140:141], off
	s_waitcnt vmcnt(8)
	s_waitcnt lgkmcnt(0)
	s_barrier
	s_setprio 1
	s_waitcnt lgkmcnt(0)
	v_mfma_f32_16x16x32_bf16 v[126:129], v[146:149], v[200:203], v[126:129]
	v_mfma_f32_16x16x32_bf16 v[122:125], v[154:157], v[200:203], v[122:125]
	v_mfma_f32_16x16x32_bf16 v[114:117], v[146:149], v[212:215], v[114:117]
	v_mfma_f32_16x16x32_bf16 v[106:109], v[154:157], v[212:215], v[106:109]
	v_mfma_f32_16x16x32_bf16 v[98:101], v[146:149], v[220:223], v[98:101]
	v_mfma_f32_16x16x32_bf16 v[90:93], v[154:157], v[220:223], v[90:93]
	v_mfma_f32_16x16x32_bf16 v[82:85], v[146:149], v[228:231], v[82:85]
	v_mfma_f32_16x16x32_bf16 v[74:77], v[154:157], v[228:231], v[74:77]
	v_mfma_f32_16x16x32_bf16 v[126:129], v[150:153], v[208:211], v[126:129]
	v_mfma_f32_16x16x32_bf16 v[122:125], v[158:161], v[208:211], v[122:125]
	v_mfma_f32_16x16x32_bf16 v[114:117], v[150:153], v[216:219], v[114:117]
	v_mfma_f32_16x16x32_bf16 v[106:109], v[158:161], v[216:219], v[106:109]
	v_mfma_f32_16x16x32_bf16 v[98:101], v[150:153], v[224:227], v[98:101]
	v_mfma_f32_16x16x32_bf16 v[90:93], v[158:161], v[224:227], v[90:93]
	v_mfma_f32_16x16x32_bf16 v[82:85], v[150:153], v[232:235], v[82:85]
	v_mfma_f32_16x16x32_bf16 v[74:77], v[158:161], v[232:235], v[74:77]
	s_setprio 0
	s_setprio 1
	v_mfma_f32_16x16x32_bf16 v[118:121], v[174:177], v[200:203], v[118:121]
	v_mfma_f32_16x16x32_bf16 v[110:113], v[182:185], v[200:203], v[110:113]
	v_mfma_f32_16x16x32_bf16 v[102:105], v[174:177], v[212:215], v[102:105]
	v_mfma_f32_16x16x32_bf16 v[94:97], v[182:185], v[212:215], v[94:97]
	v_mfma_f32_16x16x32_bf16 v[86:89], v[174:177], v[220:223], v[86:89]
	v_mfma_f32_16x16x32_bf16 v[78:81], v[182:185], v[220:223], v[78:81]
	v_mfma_f32_16x16x32_bf16 v[70:73], v[174:177], v[228:231], v[70:73]
	v_mfma_f32_16x16x32_bf16 v[66:69], v[182:185], v[228:231], v[66:69]
	v_mfma_f32_16x16x32_bf16 v[118:121], v[178:181], v[208:211], v[118:121]
	v_mfma_f32_16x16x32_bf16 v[110:113], v[186:189], v[208:211], v[110:113]
	v_mfma_f32_16x16x32_bf16 v[102:105], v[178:181], v[216:219], v[102:105]
	v_mfma_f32_16x16x32_bf16 v[94:97], v[186:189], v[216:219], v[94:97]
	s_barrier
	v_mfma_f32_16x16x32_bf16 v[86:89], v[178:181], v[224:227], v[86:89]
	v_mfma_f32_16x16x32_bf16 v[78:81], v[186:189], v[224:227], v[78:81]
	v_mfma_f32_16x16x32_bf16 v[70:73], v[178:181], v[232:235], v[70:73]
	v_mfma_f32_16x16x32_bf16 v[66:69], v[186:189], v[232:235], v[66:69]
	s_setprio 0
	s_nop 0
	s_add_i32 s70, s70, s55
	v_lshl_add_u64 v[140:141], s[50:51], 0, v[0:1]
	s_mov_b32 m0, s70
	ds_read_b128 v[200:203], v145 offset:16384
	ds_read_b128 v[208:211], v145 offset:17408
	ds_read_b128 v[212:215], v145 offset:18432
	ds_read_b128 v[216:219], v145 offset:19456
	ds_read_b128 v[220:223], v145 offset:20480
	ds_read_b128 v[224:227], v145 offset:21504
	ds_read_b128 v[228:231], v145 offset:22528
	ds_read_b128 v[232:235], v145 offset:23552
	global_load_lds_dwordx4 v[140:141], off
	s_add_i32 m0, s70, 0x2000
	s_add_u32 s70, s50, 0x40000
	v_lshl_add_u64 v[190:191], s[50:51], 0, v[130:131]
	s_addc_u32 s71, s51, 0
	s_add_i32 s76, s76, s55
	global_load_lds_dwordx4 v[190:191], off
	v_lshl_add_u64 v[236:237], s[70:71], 0, v[0:1]
	s_mov_b32 m0, s76
	v_lshl_add_u64 v[238:239], s[52:53], 0, v[132:133]
	global_load_lds_dwordx4 v[236:237], off
	v_lshl_add_u64 v[236:237], s[70:71], 0, v[130:131]
	s_add_i32 m0, s76, 0x2000
	s_nop 0
	global_load_lds_dwordx4 v[236:237], off
	v_lshl_add_u64 v[236:237], s[52:53], 0, v[134:135]
	s_mov_b32 m0, s56
	s_nop 0
	global_load_lds_dwordx4 v[236:237], off
	s_mov_b32 m0, s57
	s_nop 0
	global_load_lds_dwordx4 v[238:239], off
	s_waitcnt vmcnt(8)
	s_waitcnt lgkmcnt(0)
	s_barrier
; #define PG8_STAGE(bufoff, gbase, voff) do { _Pragma("unroll") for (int _i = 0; _i < 2; ++_i) \
;         __builtin_amdgcn_global_load_lds((const unsigned*)((const char*)(gbase) + (voff)[_i]), (PG8_LAS unsigned*)(lds + (bufoff) + ldsw + _i * 8192), 16, 0, 0); } while (0)
; #define PG8_STAGEA(bufoff, gbase, voff) do { _Pragma("unroll") for (int _i = 0; _i < 2; ++_i) \
;         __builtin_amdgcn_global_load_lds((const unsigned*)((const char*)(gbase) + (voff)[_i]), (PG8_LAS unsigned*)(lds + (bufoff) + ldsw + _i * 8192), 16, 0, A_AUX); } while (0)
; #define PG8_LDA(dst, b, h) do { _Pragma("unroll") for (int m = 0; m < 4; ++m) _Pragma("unroll") for (int k = 0; k < 2; ++k) dst[m][k] = *(const PG8_LAS bf16x8*)(lds + PG8_SA(b, h) + aoff + m * 2048 + k * 1024); } while (0)
; #define PG8_WAIT_V(n) asm volatile("s_waitcnt vmcnt(" #n ")" ::: "memory")
; #define PG8_BAR __builtin_amdgcn_s_barrier()
;     ...
;         for (int t = 0; t < nt; t += 2) {
;             const bool last = (t == nt - 2);
;             const char* a1 = cA + (size_t)(t + 1) * kstep;
;             const char* a2 = last ? nA : cA + (size_t)(t + 2) * kstep; const char* b2 = last ? nB : cB + (size_t)(t + 2) * kstep;
;             const char* a3 = a2 + kstep; const char* b3 = b2 + kstep;
;             if (last && has_next) S.a_ready(nxt);
;             if constexpr (SP2) {
;             PG8_LDB(B0, 0, 0); PG8_LDB(B1, 0, 1); PG8_SCHED; PG8_LDA(At, 0, 0); PG8_STAGEA(PG8_SA(1, 1), a1 + hstep, voffA);
;             PG8_WAIT_V(8); PG8_WAIT_L(0); PG8_BAR; PG8_MMA(0, 0, At, B0); PG8_MMA(0, 1, At, B1); PG8_BAR; PG8_SCHED;
;             PG8_LDA(At, 0, 1); PG8_STAGE(PG8_SB(0, 0), b2, voffB); PG8_STAGE(PG8_SB(0, 1), b2 + hstep, voffB); PG8_STAGEA(PG8_SA(0, 0), a2, voffA);
;             PG8_WAIT_V(8); PG8_WAIT_L(0); PG8_BAR; PG8_MMA(1, 0, At, B0); PG8_MMA(1, 1, At, B1); PG8_BAR; PG8_SCHED;
;             PG8_LDB(B0, 1, 0); PG8_LDB(B1, 1, 1); PG8_SCHED; PG8_LDA(At, 1, 0); PG8_STAGEA(PG8_SA(0, 1), a2 + hstep, voffA);
;             PG8_WAIT_V(8); PG8_WAIT_L(0); PG8_BAR; PG8_MMA(0, 0, At, B0); PG8_MMA(0, 1, At, B1); PG8_BAR; PG8_SCHED;
;             PG8_LDA(At, 1, 1); PG8_STAGE(PG8_SB(1, 0), b3, voffB); PG8_STAGE(PG8_SB(1, 1), b3 + hstep, voffB); PG8_STAGEA(PG8_SA(1, 0), a3, voffA);
;             PG8_WAIT_V(8); PG8_WAIT_L(0); PG8_BAR; PG8_MMA(1, 0, At, B0); PG8_MMA(1, 1, At, B1); PG8_BAR; PG8_SCHED;
	s_setprio 1
	s_waitcnt lgkmcnt(0)
	v_mfma_f32_16x16x32_bf16 v[62:65], v[146:149], v[200:203], v[62:65]
	v_mfma_f32_16x16x32_bf16 v[58:61], v[154:157], v[200:203], v[58:61]
	v_mfma_f32_16x16x32_bf16 v[50:53], v[146:149], v[212:215], v[50:53]
	v_mfma_f32_16x16x32_bf16 v[42:45], v[154:157], v[212:215], v[42:45]
	v_mfma_f32_16x16x32_bf16 v[34:37], v[146:149], v[220:223], v[34:37]
	v_mfma_f32_16x16x32_bf16 v[26:29], v[154:157], v[220:223], v[26:29]
	v_mfma_f32_16x16x32_bf16 v[18:21], v[146:149], v[228:231], v[18:21]
	v_mfma_f32_16x16x32_bf16 v[10:13], v[154:157], v[228:231], v[10:13]
	v_mfma_f32_16x16x32_bf16 v[62:65], v[150:153], v[208:211], v[62:65]
	v_mfma_f32_16x16x32_bf16 v[58:61], v[158:161], v[208:211], v[58:61]
	v_mfma_f32_16x16x32_bf16 v[50:53], v[150:153], v[216:219], v[50:53]
	v_mfma_f32_16x16x32_bf16 v[42:45], v[158:161], v[216:219], v[42:45]
	v_mfma_f32_16x16x32_bf16 v[34:37], v[150:153], v[224:227], v[34:37]
	v_mfma_f32_16x16x32_bf16 v[26:29], v[158:161], v[224:227], v[26:29]
	v_mfma_f32_16x16x32_bf16 v[18:21], v[150:153], v[232:235], v[18:21]
	v_mfma_f32_16x16x32_bf16 v[10:13], v[158:161], v[232:235], v[10:13]
	s_setprio 0
	s_setprio 1
	v_mfma_f32_16x16x32_bf16 v[54:57], v[174:177], v[200:203], v[54:57]
	v_mfma_f32_16x16x32_bf16 v[46:49], v[182:185], v[200:203], v[46:49]
	v_mfma_f32_16x16x32_bf16 v[38:41], v[174:177], v[212:215], v[38:41]
	v_mfma_f32_16x16x32_bf16 v[30:33], v[182:185], v[212:215], v[30:33]
	v_mfma_f32_16x16x32_bf16 v[22:25], v[174:177], v[220:223], v[22:25]
	v_mfma_f32_16x16x32_bf16 v[14:17], v[182:185], v[220:223], v[14:17]
	v_mfma_f32_16x16x32_bf16 v[6:9], v[174:177], v[228:231], v[6:9]
	v_mfma_f32_16x16x32_bf16 v[2:5], v[182:185], v[228:231], v[2:5]
	v_mfma_f32_16x16x32_bf16 v[54:57], v[178:181], v[208:211], v[54:57]
	v_mfma_f32_16x16x32_bf16 v[46:49], v[186:189], v[208:211], v[46:49]
	v_mfma_f32_16x16x32_bf16 v[38:41], v[178:181], v[216:219], v[38:41]
	v_mfma_f32_16x16x32_bf16 v[30:33], v[186:189], v[216:219], v[30:33]
	s_barrier
	v_mfma_f32_16x16x32_bf16 v[22:25], v[178:181], v[224:227], v[22:25]
	v_mfma_f32_16x16x32_bf16 v[14:17], v[186:189], v[224:227], v[14:17]
	v_mfma_f32_16x16x32_bf16 v[6:9], v[178:181], v[232:235], v[6:9]
	v_mfma_f32_16x16x32_bf16 v[2:5], v[186:189], v[232:235], v[2:5]
	s_setprio 0
	s_nop 0
	s_add_i32 s70, 0, 0x18000
	s_add_i32 s71, 0, 0x1c000
	v_add_u32_e32 v158, s70, v143
	v_add_u32_e32 v186, s71, v143
	ds_read_b128 v[146:149], v158
	ds_read_b128 v[150:153], v158 offset:1024
	ds_read_b128 v[154:157], v158 offset:2048
	ds_read_b128 v[158:161], v158 offset:3072
	ds_read_b128 v[174:177], v186
	ds_read_b128 v[178:181], v186 offset:1024
	ds_read_b128 v[182:185], v186 offset:2048
	ds_read_b128 v[186:189], v186 offset:3072
	s_add_u32 s52, s52, 0x40000
	s_addc_u32 s53, s53, 0
	s_mov_b32 m0, s58
	v_lshl_add_u64 v[240:241], s[52:53], 0, v[134:135]
	ds_read_b128 v[200:203], v145 offset:32768
	ds_read_b128 v[208:211], v145 offset:33792
	ds_read_b128 v[212:215], v145 offset:34816
	ds_read_b128 v[216:219], v145 offset:35840
	ds_read_b128 v[220:223], v145 offset:36864
	ds_read_b128 v[224:227], v145 offset:37888
	ds_read_b128 v[228:231], v145 offset:38912
	ds_read_b128 v[232:235], v145 offset:39936
	global_load_lds_dwordx4 v[240:241], off
	v_lshl_add_u64 v[240:241], s[52:53], 0, v[132:133]
	s_mov_b32 m0, s59
	s_nop 0
	global_load_lds_dwordx4 v[240:241], off
	s_waitcnt vmcnt(8)
	s_waitcnt lgkmcnt(0)
	s_barrier
	s_setprio 1
	s_waitcnt lgkmcnt(0)
	v_mfma_f32_16x16x32_bf16 v[126:129], v[146:149], v[200:203], v[126:129]
	v_mfma_f32_16x16x32_bf16 v[122:125], v[154:157], v[200:203], v[122:125]
	v_mfma_f32_16x16x32_bf16 v[114:117], v[146:149], v[212:215], v[114:117]
	v_mfma_f32_16x16x32_bf16 v[106:109], v[154:157], v[212:215], v[106:109]
	v_mfma_f32_16x16x32_bf16 v[98:101], v[146:149], v[220:223], v[98:101]
	v_mfma_f32_16x16x32_bf16 v[90:93], v[154:157], v[220:223], v[90:93]
	v_mfma_f32_16x16x32_bf16 v[82:85], v[146:149], v[228:231], v[82:85]
	v_mfma_f32_16x16x32_bf16 v[74:77], v[154:157], v[228:231], v[74:77]
	v_mfma_f32_16x16x32_bf16 v[126:129], v[150:153], v[208:211], v[126:129]
	v_mfma_f32_16x16x32_bf16 v[122:125], v[158:161], v[208:211], v[122:125]
	v_mfma_f32_16x16x32_bf16 v[114:117], v[150:153], v[216:219], v[114:117]
	v_mfma_f32_16x16x32_bf16 v[106:109], v[158:161], v[216:219], v[106:109]
	v_mfma_f32_16x16x32_bf16 v[98:101], v[150:153], v[224:227], v[98:101]
	v_mfma_f32_16x16x32_bf16 v[90:93], v[158:161], v[224:227], v[90:93]
	v_mfma_f32_16x16x32_bf16 v[82:85], v[150:153], v[232:235], v[82:85]
	v_mfma_f32_16x16x32_bf16 v[74:77], v[158:161], v[232:235], v[74:77]
	s_setprio 0
	s_setprio 1
	v_mfma_f32_16x16x32_bf16 v[118:121], v[174:177], v[200:203], v[118:121]
	v_mfma_f32_16x16x32_bf16 v[110:113], v[182:185], v[200:203], v[110:113]
	v_mfma_f32_16x16x32_bf16 v[102:105], v[174:177], v[212:215], v[102:105]
	v_mfma_f32_16x16x32_bf16 v[94:97], v[182:185], v[212:215], v[94:97]
	v_mfma_f32_16x16x32_bf16 v[86:89], v[174:177], v[220:223], v[86:89]
	v_mfma_f32_16x16x32_bf16 v[78:81], v[182:185], v[220:223], v[78:81]
	v_mfma_f32_16x16x32_bf16 v[70:73], v[174:177], v[228:231], v[70:73]
	v_mfma_f32_16x16x32_bf16 v[66:69], v[182:185], v[228:231], v[66:69]
	v_mfma_f32_16x16x32_bf16 v[118:121], v[178:181], v[208:211], v[118:121]
	v_mfma_f32_16x16x32_bf16 v[110:113], v[186:189], v[208:211], v[110:113]
	v_mfma_f32_16x16x32_bf16 v[102:105], v[178:181], v[216:219], v[102:105]
	v_mfma_f32_16x16x32_bf16 v[94:97], v[186:189], v[216:219], v[94:97]
	s_barrier
; #define PG8_STAGE(bufoff, gbase, voff) do { _Pragma("unroll") for (int _i = 0; _i < 2; ++_i) \
;         __builtin_amdgcn_global_load_lds((const unsigned*)((const char*)(gbase) + (voff)[_i]), (PG8_LAS unsigned*)(lds + (bufoff) + ldsw + _i * 8192), 16, 0, 0); } while (0)
; #define PG8_STAGEA(bufoff, gbase, voff) do { _Pragma("unroll") for (int _i = 0; _i < 2; ++_i) \
;         __builtin_amdgcn_global_load_lds((const unsigned*)((const char*)(gbase) + (voff)[_i]), (PG8_LAS unsigned*)(lds + (bufoff) + ldsw + _i * 8192), 16, 0, A_AUX); } while (0)
; #define PG8_LDA(dst, b, h) do { _Pragma("unroll") for (int m = 0; m < 4; ++m) _Pragma("unroll") for (int k = 0; k < 2; ++k) dst[m][k] = *(const PG8_LAS bf16x8*)(lds + PG8_SA(b, h) + aoff + m * 2048 + k * 1024); } while (0)
; #define PG8_WAIT_V(n) asm volatile("s_waitcnt vmcnt(" #n ")" ::: "memory")
; #define PG8_BAR __builtin_amdgcn_s_barrier()
;     ...
;         for (int t = 0; t < nt; t += 2) {
;             const bool last = (t == nt - 2);
;             const char* a1 = cA + (size_t)(t + 1) * kstep;
;             const char* a2 = last ? nA : cA + (size_t)(t + 2) * kstep; const char* b2 = last ? nB : cB + (size_t)(t + 2) * kstep;
;             const char* a3 = a2 + kstep; const char* b3 = b2 + kstep;
;             if (last && has_next) S.a_ready(nxt);
;             if constexpr (SP2) {
;             PG8_LDB(B0, 0, 0); PG8_LDB(B1, 0, 1); PG8_SCHED; PG8_LDA(At, 0, 0); PG8_STAGEA(PG8_SA(1, 1), a1 + hstep, voffA);
;             PG8_WAIT_V(8); PG8_WAIT_L(0); PG8_BAR; PG8_MMA(0, 0, At, B0); PG8_MMA(0, 1, At, B1); PG8_BAR; PG8_SCHED;
;             PG8_LDA(At, 0, 1); PG8_STAGE(PG8_SB(0, 0), b2, voffB); PG8_STAGE(PG8_SB(0, 1), b2 + hstep, voffB); PG8_STAGEA(PG8_SA(0, 0), a2, voffA);
;             PG8_WAIT_V(8); PG8_WAIT_L(0); PG8_BAR; PG8_MMA(1, 0, At, B0); PG8_MMA(1, 1, At, B1); PG8_BAR; PG8_SCHED;
;             PG8_LDB(B0, 1, 0); PG8_LDB(B1, 1, 1); PG8_SCHED; PG8_LDA(At, 1, 0); PG8_STAGEA(PG8_SA(0, 1), a2 + hstep, voffA);
;             PG8_WAIT_V(8); PG8_WAIT_L(0); PG8_BAR; PG8_MMA(0, 0, At, B0); PG8_MMA(0, 1, At, B1); PG8_BAR; PG8_SCHED;
;             PG8_LDA(At, 1, 1); PG8_STAGE(PG8_SB(1, 0), b3, voffB); PG8_STAGE(PG8_SB(1, 1), b3 + hstep, voffB); PG8_STAGEA(PG8_SA(1, 0), a3, voffA);
;             PG8_WAIT_V(8); PG8_WAIT_L(0); PG8_BAR; PG8_MMA(1, 0, At, B0); PG8_MMA(1, 1, At, B1); PG8_BAR; PG8_SCHED;
	v_mfma_f32_16x16x32_bf16 v[86:89], v[178:181], v[224:227], v[86:89]
	v_mfma_f32_16x16x32_bf16 v[78:81], v[186:189], v[224:227], v[78:81]
	v_mfma_f32_16x16x32_bf16 v[70:73], v[178:181], v[232:235], v[70:73]
	v_mfma_f32_16x16x32_bf16 v[66:69], v[186:189], v[232:235], v[66:69]
	s_setprio 0
	s_nop 0
	s_add_i32 s52, s70, s55
	v_lshl_add_u64 v[140:141], v[140:141], 0, s[8:9]
	s_mov_b32 m0, s52
	ds_read_b128 v[200:203], v145 offset:49152
	ds_read_b128 v[208:211], v145 offset:50176
	ds_read_b128 v[212:215], v145 offset:51200
	ds_read_b128 v[216:219], v145 offset:52224
	ds_read_b128 v[220:223], v145 offset:53248
	ds_read_b128 v[224:227], v145 offset:54272
	ds_read_b128 v[228:231], v145 offset:55296
	ds_read_b128 v[232:235], v145 offset:56320
	global_load_lds_dwordx4 v[140:141], off
	s_add_i32 m0, s52, 0x2000
	s_add_u32 s50, s50, 0x40080
	v_lshl_add_u64 v[140:141], v[190:191], 0, s[8:9]
	s_addc_u32 s51, s51, 0
	s_add_i32 s52, s71, s55
	global_load_lds_dwordx4 v[140:141], off
	v_lshl_add_u64 v[140:141], s[50:51], 0, v[0:1]
	s_mov_b32 m0, s52
	s_nop 0
	global_load_lds_dwordx4 v[140:141], off
	v_lshl_add_u64 v[140:141], s[50:51], 0, v[130:131]
	s_add_i32 m0, s52, 0x2000
	s_nop 0
	global_load_lds_dwordx4 v[140:141], off
	v_lshl_add_u64 v[140:141], v[236:237], 0, s[8:9]
	s_mov_b32 m0, s60
	s_nop 0
	global_load_lds_dwordx4 v[140:141], off
	v_lshl_add_u64 v[140:141], v[238:239], 0, s[8:9]
	s_mov_b32 m0, s61
	s_nop 0
	global_load_lds_dwordx4 v[140:141], off
	s_waitcnt vmcnt(8)
	s_waitcnt lgkmcnt(0)
	s_barrier
	s_setprio 1
	s_waitcnt lgkmcnt(0)
	v_mfma_f32_16x16x32_bf16 v[62:65], v[146:149], v[200:203], v[62:65]
	v_mfma_f32_16x16x32_bf16 v[58:61], v[154:157], v[200:203], v[58:61]
	v_mfma_f32_16x16x32_bf16 v[50:53], v[146:149], v[212:215], v[50:53]
	v_mfma_f32_16x16x32_bf16 v[42:45], v[154:157], v[212:215], v[42:45]
	v_mfma_f32_16x16x32_bf16 v[34:37], v[146:149], v[220:223], v[34:37]
	v_mfma_f32_16x16x32_bf16 v[26:29], v[154:157], v[220:223], v[26:29]
	v_mfma_f32_16x16x32_bf16 v[18:21], v[146:149], v[228:231], v[18:21]
	v_mfma_f32_16x16x32_bf16 v[10:13], v[154:157], v[228:231], v[10:13]
	v_mfma_f32_16x16x32_bf16 v[62:65], v[150:153], v[208:211], v[62:65]
	v_mfma_f32_16x16x32_bf16 v[58:61], v[158:161], v[208:211], v[58:61]
	v_mfma_f32_16x16x32_bf16 v[50:53], v[150:153], v[216:219], v[50:53]
	v_mfma_f32_16x16x32_bf16 v[42:45], v[158:161], v[216:219], v[42:45]
	v_mfma_f32_16x16x32_bf16 v[34:37], v[150:153], v[224:227], v[34:37]
	v_mfma_f32_16x16x32_bf16 v[26:29], v[158:161], v[224:227], v[26:29]
	v_mfma_f32_16x16x32_bf16 v[18:21], v[150:153], v[232:235], v[18:21]
	v_mfma_f32_16x16x32_bf16 v[10:13], v[158:161], v[232:235], v[10:13]
	s_setprio 0
	s_setprio 1
	v_mfma_f32_16x16x32_bf16 v[54:57], v[174:177], v[200:203], v[54:57]
	v_mfma_f32_16x16x32_bf16 v[46:49], v[182:185], v[200:203], v[46:49]
	v_mfma_f32_16x16x32_bf16 v[38:41], v[174:177], v[212:215], v[38:41]
	v_mfma_f32_16x16x32_bf16 v[30:33], v[182:185], v[212:215], v[30:33]
	v_mfma_f32_16x16x32_bf16 v[22:25], v[174:177], v[220:223], v[22:25]
	v_mfma_f32_16x16x32_bf16 v[14:17], v[182:185], v[220:223], v[14:17]
	v_mfma_f32_16x16x32_bf16 v[6:9], v[174:177], v[228:231], v[6:9]
	v_mfma_f32_16x16x32_bf16 v[2:5], v[182:185], v[228:231], v[2:5]
	v_mfma_f32_16x16x32_bf16 v[54:57], v[178:181], v[208:211], v[54:57]
	v_mfma_f32_16x16x32_bf16 v[46:49], v[186:189], v[208:211], v[46:49]
	v_mfma_f32_16x16x32_bf16 v[38:41], v[178:181], v[216:219], v[38:41]
	v_mfma_f32_16x16x32_bf16 v[30:33], v[186:189], v[216:219], v[30:33]
	s_barrier
	v_mfma_f32_16x16x32_bf16 v[22:25], v[178:181], v[224:227], v[22:25]
	v_mfma_f32_16x16x32_bf16 v[14:17], v[186:189], v[224:227], v[14:17]
	v_mfma_f32_16x16x32_bf16 v[6:9], v[178:181], v[232:235], v[6:9]
	v_mfma_f32_16x16x32_bf16 v[2:5], v[186:189], v[232:235], v[2:5]
	s_setprio 0
	s_nop 0
	s_add_i32 s73, s73, 2
	s_add_u32 s48, s48, 0x100
	s_addc_u32 s49, s49, 0
	s_add_u32 s65, s65, 0x100
	s_addc_u32 s72, s72, 0
	s_cmp_gt_u32 s73, 13
	s_cbranch_scc0 .LBB0_443
	s_and_b64 vcc, exec, s[36:37]
	s_cbranch_vccz .LBB0_446
	s_barrier

; #define PG8_STAGE(bufoff, gbase, voff) do { _Pragma("unroll") for (int _i = 0; _i < 2; ++_i) \
;         __builtin_amdgcn_global_load_lds((const unsigned*)((const char*)(gbase) + (voff)[_i]), (PG8_LAS unsigned*)(lds + (bufoff) + ldsw + _i * 8192), 16, 0, 0); } while (0)
; #define PG8_STAGEA(bufoff, gbase, voff) do { _Pragma("unroll") for (int _i = 0; _i < 2; ++_i) \
;         __builtin_amdgcn_global_load_lds((const unsigned*)((const char*)(gbase) + (voff)[_i]), (PG8_LAS unsigned*)(lds + (bufoff) + ldsw + _i * 8192), 16, 0, A_AUX); } while (0)
; #define PG8_LDA(dst, b, h) do { _Pragma("unroll") for (int m = 0; m < 4; ++m) _Pragma("unroll") for (int k = 0; k < 2; ++k) dst[m][k] = *(const PG8_LAS bf16x8*)(lds + PG8_SA(b, h) + aoff + m * 2048 + k * 1024); } while (0)
; #define PG8_WAIT_V(n) asm volatile("s_waitcnt vmcnt(" #n ")" ::: "memory")
; #define PG8_BAR __builtin_amdgcn_s_barrier()
;     ...
;         for (int t = 0; t < nt; t += 2) {
;             const bool last = (t == nt - 2);
;             const char* a1 = cA + (size_t)(t + 1) * kstep;
;             const char* a2 = last ? nA : cA + (size_t)(t + 2) * kstep; const char* b2 = last ? nB : cB + (size_t)(t + 2) * kstep;
;             const char* a3 = a2 + kstep; const char* b3 = b2 + kstep;
;             if (last && has_next) S.a_ready(nxt);
;             if constexpr (SP2) {
;             PG8_LDB(B0, 0, 0); PG8_LDB(B1, 0, 1); PG8_SCHED; PG8_LDA(At, 0, 0); PG8_STAGEA(PG8_SA(1, 1), a1 + hstep, voffA);
;             PG8_WAIT_V(8); PG8_WAIT_L(0); PG8_BAR; PG8_MMA(0, 0, At, B0); PG8_MMA(0, 1, At, B1); PG8_BAR; PG8_SCHED;
;             PG8_LDA(At, 0, 1); PG8_STAGE(PG8_SB(0, 0), b2, voffB); PG8_STAGE(PG8_SB(0, 1), b2 + hstep, voffB); PG8_STAGEA(PG8_SA(0, 0), a2, voffA);
;             PG8_WAIT_V(8); PG8_WAIT_L(0); PG8_BAR; PG8_MMA(1, 0, At, B0); PG8_MMA(1, 1, At, B1); PG8_BAR; PG8_SCHED;
;             PG8_LDB(B0, 1, 0); PG8_LDB(B1, 1, 1); PG8_SCHED; PG8_LDA(At, 1, 0); PG8_STAGEA(PG8_SA(0, 1), a2 + hstep, voffA);
;             PG8_WAIT_V(8); PG8_WAIT_L(0); PG8_BAR; PG8_MMA(0, 0, At, B0); PG8_MMA(0, 1, At, B1); PG8_BAR; PG8_SCHED;
;             PG8_LDA(At, 1, 1); PG8_STAGE(PG8_SB(1, 0), b3, voffB); PG8_STAGE(PG8_SB(1, 1), b3 + hstep, voffB); PG8_STAGEA(PG8_SA(1, 0), a3, voffA);
;             PG8_WAIT_V(8); PG8_WAIT_L(0); PG8_BAR; PG8_MMA(1, 0, At, B0); PG8_MMA(1, 1, At, B1); PG8_BAR; PG8_SCHED;
.LBB0_580:
	s_add_u32 s52, s50, 0xfffc0080
	s_addc_u32 s53, s51, -1
	s_add_i32 s70, 0, 0x10000
	s_cmp_eq_u32 vcc_lo, 12
	s_cselect_b32 s55, s16, s53
	s_cselect_b32 s54, s17, s52
	v_add_u32_e32 v140, s70, v143
	s_cselect_b32 s53, s43, s76
	s_cselect_b32 s52, s45, s73
	s_add_i32 vcc_hi, 0, 0x14000
	ds_read_b128 v[146:149], v140
	ds_read_b128 v[150:153], v140 offset:1024
	ds_read_b128 v[154:157], v140 offset:2048
	ds_read_b128 v[158:161], v140 offset:3072
	v_add_u32_e32 v140, vcc_hi, v143
	ds_read_b128 v[174:177], v140
	ds_read_b128 v[178:181], v140 offset:1024
	ds_read_b128 v[182:185], v140 offset:2048
	ds_read_b128 v[186:189], v140 offset:3072
	v_lshl_add_u64 v[140:141], s[50:51], 0, v[136:137]
	s_add_i32 m0, s58, 0xc000
	ds_read_b128 v[200:203], v145
	ds_read_b128 v[208:211], v145 offset:1024
	ds_read_b128 v[212:215], v145 offset:2048
	ds_read_b128 v[216:219], v145 offset:3072
	ds_read_b128 v[220:223], v145 offset:4096
	ds_read_b128 v[224:227], v145 offset:5120
	ds_read_b128 v[228:231], v145 offset:6144
	ds_read_b128 v[232:235], v145 offset:7168
	global_load_lds_dwordx4 v[140:141], off
	v_lshl_add_u64 v[140:141], s[50:51], 0, v[138:139]
	s_add_i32 m0, s58, 0xe000
	s_nop 0
	global_load_lds_dwordx4 v[140:141], off
	s_waitcnt vmcnt(8)
	s_waitcnt lgkmcnt(0)
	s_barrier
	s_setprio 1
	s_waitcnt lgkmcnt(0)
	v_mfma_f32_16x16x32_bf16 v[126:129], v[146:149], v[200:203], v[126:129]
	v_mfma_f32_16x16x32_bf16 v[122:125], v[154:157], v[200:203], v[122:125]
	v_mfma_f32_16x16x32_bf16 v[110:113], v[146:149], v[212:215], v[110:113]
	v_mfma_f32_16x16x32_bf16 v[106:109], v[154:157], v[212:215], v[106:109]
	v_mfma_f32_16x16x32_bf16 v[94:97], v[146:149], v[220:223], v[94:97]
	v_mfma_f32_16x16x32_bf16 v[90:93], v[154:157], v[220:223], v[90:93]
	v_mfma_f32_16x16x32_bf16 v[78:81], v[146:149], v[228:231], v[78:81]
	v_mfma_f32_16x16x32_bf16 v[74:77], v[154:157], v[228:231], v[74:77]
	v_mfma_f32_16x16x32_bf16 v[126:129], v[150:153], v[208:211], v[126:129]
	v_mfma_f32_16x16x32_bf16 v[122:125], v[158:161], v[208:211], v[122:125]
	v_mfma_f32_16x16x32_bf16 v[110:113], v[150:153], v[216:219], v[110:113]
	v_mfma_f32_16x16x32_bf16 v[106:109], v[158:161], v[216:219], v[106:109]
	v_mfma_f32_16x16x32_bf16 v[94:97], v[150:153], v[224:227], v[94:97]
	v_mfma_f32_16x16x32_bf16 v[90:93], v[158:161], v[224:227], v[90:93]
	v_mfma_f32_16x16x32_bf16 v[78:81], v[150:153], v[232:235], v[78:81]
	v_mfma_f32_16x16x32_bf16 v[74:77], v[158:161], v[232:235], v[74:77]
	s_setprio 0
	s_setprio 1
	v_mfma_f32_16x16x32_bf16 v[118:121], v[174:177], v[200:203], v[118:121]
	v_mfma_f32_16x16x32_bf16 v[114:117], v[182:185], v[200:203], v[114:117]
	v_mfma_f32_16x16x32_bf16 v[102:105], v[174:177], v[212:215], v[102:105]
	v_mfma_f32_16x16x32_bf16 v[98:101], v[182:185], v[212:215], v[98:101]
	v_mfma_f32_16x16x32_bf16 v[86:89], v[174:177], v[220:223], v[86:89]
	v_mfma_f32_16x16x32_bf16 v[82:85], v[182:185], v[220:223], v[82:85]
	v_mfma_f32_16x16x32_bf16 v[70:73], v[174:177], v[228:231], v[70:73]
	v_mfma_f32_16x16x32_bf16 v[66:69], v[182:185], v[228:231], v[66:69]
	v_mfma_f32_16x16x32_bf16 v[118:121], v[178:181], v[208:211], v[118:121]
	v_mfma_f32_16x16x32_bf16 v[114:117], v[186:189], v[208:211], v[114:117]
	v_mfma_f32_16x16x32_bf16 v[102:105], v[178:181], v[216:219], v[102:105]
	v_mfma_f32_16x16x32_bf16 v[98:101], v[186:189], v[216:219], v[98:101]
	s_barrier
	v_mfma_f32_16x16x32_bf16 v[86:89], v[178:181], v[224:227], v[86:89]
	v_mfma_f32_16x16x32_bf16 v[82:85], v[186:189], v[224:227], v[82:85]
	v_mfma_f32_16x16x32_bf16 v[70:73], v[178:181], v[232:235], v[70:73]
	v_mfma_f32_16x16x32_bf16 v[66:69], v[186:189], v[232:235], v[66:69]
	s_setprio 0
	s_nop 0
	s_add_i32 s70, s70, s57
	v_lshl_add_u64 v[140:141], s[52:53], 0, v[0:1]
	s_mov_b32 m0, s70
	ds_read_b128 v[200:203], v145 offset:16384
	ds_read_b128 v[208:211], v145 offset:17408
	ds_read_b128 v[212:215], v145 offset:18432
	ds_read_b128 v[216:219], v145 offset:19456
	ds_read_b128 v[220:223], v145 offset:20480
	ds_read_b128 v[224:227], v145 offset:21504
	ds_read_b128 v[228:231], v145 offset:22528
	ds_read_b128 v[232:235], v145 offset:23552
	global_load_lds_dwordx4 v[140:141], off
	s_add_i32 m0, s70, 0x2000
	s_add_u32 s70, s52, 0x40000
	v_lshl_add_u64 v[190:191], s[52:53], 0, v[130:131]
	s_addc_u32 s71, s53, 0
	s_add_i32 vcc_hi, vcc_hi, s57
	global_load_lds_dwordx4 v[190:191], off
	v_lshl_add_u64 v[236:237], s[70:71], 0, v[0:1]
	s_mov_b32 m0, vcc_hi
	v_lshl_add_u64 v[238:239], s[54:55], 0, v[132:133]
	global_load_lds_dwordx4 v[236:237], off
	v_lshl_add_u64 v[236:237], s[70:71], 0, v[130:131]
	s_add_i32 m0, vcc_hi, 0x2000
	s_nop 0
	global_load_lds_dwordx4 v[236:237], off
	v_lshl_add_u64 v[236:237], s[54:55], 0, v[134:135]
	s_mov_b32 m0, s58
	s_nop 0
	global_load_lds_dwordx4 v[236:237], off
	s_mov_b32 m0, s59
	s_nop 0
	global_load_lds_dwordx4 v[238:239], off
	s_waitcnt vmcnt(8)
	s_waitcnt lgkmcnt(0)
	s_barrier
; #define PG8_STAGE(bufoff, gbase, voff) do { _Pragma("unroll") for (int _i = 0; _i < 2; ++_i) \
;         __builtin_amdgcn_global_load_lds((const unsigned*)((const char*)(gbase) + (voff)[_i]), (PG8_LAS unsigned*)(lds + (bufoff) + ldsw + _i * 8192), 16, 0, 0); } while (0)
; #define PG8_STAGEA(bufoff, gbase, voff) do { _Pragma("unroll") for (int _i = 0; _i < 2; ++_i) \
;         __builtin_amdgcn_global_load_lds((const unsigned*)((const char*)(gbase) + (voff)[_i]), (PG8_LAS unsigned*)(lds + (bufoff) + ldsw + _i * 8192), 16, 0, A_AUX); } while (0)
; #define PG8_LDA(dst, b, h) do { _Pragma("unroll") for (int m = 0; m < 4; ++m) _Pragma("unroll") for (int k = 0; k < 2; ++k) dst[m][k] = *(const PG8_LAS bf16x8*)(lds + PG8_SA(b, h) + aoff + m * 2048 + k * 1024); } while (0)
; #define PG8_WAIT_V(n) asm volatile("s_waitcnt vmcnt(" #n ")" ::: "memory")
; #define PG8_BAR __builtin_amdgcn_s_barrier()
;     ...
;         for (int t = 0; t < nt; t += 2) {
;             const bool last = (t == nt - 2);
;             const char* a1 = cA + (size_t)(t + 1) * kstep;
;             const char* a2 = last ? nA : cA + (size_t)(t + 2) * kstep; const char* b2 = last ? nB : cB + (size_t)(t + 2) * kstep;
;             const char* a3 = a2 + kstep; const char* b3 = b2 + kstep;
;             if (last && has_next) S.a_ready(nxt);
;             if constexpr (SP2) {
;             PG8_LDB(B0, 0, 0); PG8_LDB(B1, 0, 1); PG8_SCHED; PG8_LDA(At, 0, 0); PG8_STAGEA(PG8_SA(1, 1), a1 + hstep, voffA);
;             PG8_WAIT_V(8); PG8_WAIT_L(0); PG8_BAR; PG8_MMA(0, 0, At, B0); PG8_MMA(0, 1, At, B1); PG8_BAR; PG8_SCHED;
;             PG8_LDA(At, 0, 1); PG8_STAGE(PG8_SB(0, 0), b2, voffB); PG8_STAGE(PG8_SB(0, 1), b2 + hstep, voffB); PG8_STAGEA(PG8_SA(0, 0), a2, voffA);
;             PG8_WAIT_V(8); PG8_WAIT_L(0); PG8_BAR; PG8_MMA(1, 0, At, B0); PG8_MMA(1, 1, At, B1); PG8_BAR; PG8_SCHED;
;             PG8_LDB(B0, 1, 0); PG8_LDB(B1, 1, 1); PG8_SCHED; PG8_LDA(At, 1, 0); PG8_STAGEA(PG8_SA(0, 1), a2 + hstep, voffA);
;             PG8_WAIT_V(8); PG8_WAIT_L(0); PG8_BAR; PG8_MMA(0, 0, At, B0); PG8_MMA(0, 1, At, B1); PG8_BAR; PG8_SCHED;
;             PG8_LDA(At, 1, 1); PG8_STAGE(PG8_SB(1, 0), b3, voffB); PG8_STAGE(PG8_SB(1, 1), b3 + hstep, voffB); PG8_STAGEA(PG8_SA(1, 0), a3, voffA);
;             PG8_WAIT_V(8); PG8_WAIT_L(0); PG8_BAR; PG8_MMA(1, 0, At, B0); PG8_MMA(1, 1, At, B1); PG8_BAR; PG8_SCHED;
	s_setprio 1
	s_waitcnt lgkmcnt(0)
	v_mfma_f32_16x16x32_bf16 v[62:65], v[146:149], v[200:203], v[62:65]
	v_mfma_f32_16x16x32_bf16 v[58:61], v[154:157], v[200:203], v[58:61]
	v_mfma_f32_16x16x32_bf16 v[46:49], v[146:149], v[212:215], v[46:49]
	v_mfma_f32_16x16x32_bf16 v[42:45], v[154:157], v[212:215], v[42:45]
	v_mfma_f32_16x16x32_bf16 v[30:33], v[146:149], v[220:223], v[30:33]
	v_mfma_f32_16x16x32_bf16 v[26:29], v[154:157], v[220:223], v[26:29]
	v_mfma_f32_16x16x32_bf16 v[14:17], v[146:149], v[228:231], v[14:17]
	v_mfma_f32_16x16x32_bf16 v[10:13], v[154:157], v[228:231], v[10:13]
	v_mfma_f32_16x16x32_bf16 v[62:65], v[150:153], v[208:211], v[62:65]
	v_mfma_f32_16x16x32_bf16 v[58:61], v[158:161], v[208:211], v[58:61]
	v_mfma_f32_16x16x32_bf16 v[46:49], v[150:153], v[216:219], v[46:49]
	v_mfma_f32_16x16x32_bf16 v[42:45], v[158:161], v[216:219], v[42:45]
	v_mfma_f32_16x16x32_bf16 v[30:33], v[150:153], v[224:227], v[30:33]
	v_mfma_f32_16x16x32_bf16 v[26:29], v[158:161], v[224:227], v[26:29]
	v_mfma_f32_16x16x32_bf16 v[14:17], v[150:153], v[232:235], v[14:17]
	v_mfma_f32_16x16x32_bf16 v[10:13], v[158:161], v[232:235], v[10:13]
	s_setprio 0
	s_setprio 1
	v_mfma_f32_16x16x32_bf16 v[54:57], v[174:177], v[200:203], v[54:57]
	v_mfma_f32_16x16x32_bf16 v[50:53], v[182:185], v[200:203], v[50:53]
	v_mfma_f32_16x16x32_bf16 v[38:41], v[174:177], v[212:215], v[38:41]
	v_mfma_f32_16x16x32_bf16 v[34:37], v[182:185], v[212:215], v[34:37]
	v_mfma_f32_16x16x32_bf16 v[22:25], v[174:177], v[220:223], v[22:25]
	v_mfma_f32_16x16x32_bf16 v[18:21], v[182:185], v[220:223], v[18:21]
	v_mfma_f32_16x16x32_bf16 v[6:9], v[174:177], v[228:231], v[6:9]
	v_mfma_f32_16x16x32_bf16 v[2:5], v[182:185], v[228:231], v[2:5]
	v_mfma_f32_16x16x32_bf16 v[54:57], v[178:181], v[208:211], v[54:57]
	v_mfma_f32_16x16x32_bf16 v[50:53], v[186:189], v[208:211], v[50:53]
	v_mfma_f32_16x16x32_bf16 v[38:41], v[178:181], v[216:219], v[38:41]
	v_mfma_f32_16x16x32_bf16 v[34:37], v[186:189], v[216:219], v[34:37]
	s_barrier
	v_mfma_f32_16x16x32_bf16 v[22:25], v[178:181], v[224:227], v[22:25]
	v_mfma_f32_16x16x32_bf16 v[18:21], v[186:189], v[224:227], v[18:21]
	v_mfma_f32_16x16x32_bf16 v[6:9], v[178:181], v[232:235], v[6:9]
	v_mfma_f32_16x16x32_bf16 v[2:5], v[186:189], v[232:235], v[2:5]
	s_setprio 0
	s_nop 0
	s_add_i32 s70, 0, 0x18000
	s_add_i32 s71, 0, 0x1c000
	v_add_u32_e32 v158, s70, v143
	v_add_u32_e32 v186, s71, v143
	ds_read_b128 v[146:149], v158
	ds_read_b128 v[150:153], v158 offset:1024
	ds_read_b128 v[154:157], v158 offset:2048
	ds_read_b128 v[158:161], v158 offset:3072
	ds_read_b128 v[174:177], v186
	ds_read_b128 v[178:181], v186 offset:1024
	ds_read_b128 v[182:185], v186 offset:2048
	ds_read_b128 v[186:189], v186 offset:3072
	s_add_u32 s54, s54, 0x40000
	s_addc_u32 s55, s55, 0
	s_mov_b32 m0, s60
	v_lshl_add_u64 v[240:241], s[54:55], 0, v[134:135]
	ds_read_b128 v[200:203], v145 offset:32768
	ds_read_b128 v[208:211], v145 offset:33792
	ds_read_b128 v[212:215], v145 offset:34816
	ds_read_b128 v[216:219], v145 offset:35840
	ds_read_b128 v[220:223], v145 offset:36864
	ds_read_b128 v[224:227], v145 offset:37888
	ds_read_b128 v[228:231], v145 offset:38912
	ds_read_b128 v[232:235], v145 offset:39936
	global_load_lds_dwordx4 v[240:241], off
	v_lshl_add_u64 v[240:241], s[54:55], 0, v[132:133]
	s_mov_b32 m0, s61
	s_nop 0
	global_load_lds_dwordx4 v[240:241], off
	s_waitcnt vmcnt(8)
	s_waitcnt lgkmcnt(0)
	s_barrier
	s_setprio 1
	s_waitcnt lgkmcnt(0)
	v_mfma_f32_16x16x32_bf16 v[126:129], v[146:149], v[200:203], v[126:129]
	v_mfma_f32_16x16x32_bf16 v[122:125], v[154:157], v[200:203], v[122:125]
	v_mfma_f32_16x16x32_bf16 v[110:113], v[146:149], v[212:215], v[110:113]
	v_mfma_f32_16x16x32_bf16 v[106:109], v[154:157], v[212:215], v[106:109]
	v_mfma_f32_16x16x32_bf16 v[94:97], v[146:149], v[220:223], v[94:97]
	v_mfma_f32_16x16x32_bf16 v[90:93], v[154:157], v[220:223], v[90:93]
	v_mfma_f32_16x16x32_bf16 v[78:81], v[146:149], v[228:231], v[78:81]
	v_mfma_f32_16x16x32_bf16 v[74:77], v[154:157], v[228:231], v[74:77]
	v_mfma_f32_16x16x32_bf16 v[126:129], v[150:153], v[208:211], v[126:129]
	v_mfma_f32_16x16x32_bf16 v[122:125], v[158:161], v[208:211], v[122:125]
	v_mfma_f32_16x16x32_bf16 v[110:113], v[150:153], v[216:219], v[110:113]
	v_mfma_f32_16x16x32_bf16 v[106:109], v[158:161], v[216:219], v[106:109]
	v_mfma_f32_16x16x32_bf16 v[94:97], v[150:153], v[224:227], v[94:97]
	v_mfma_f32_16x16x32_bf16 v[90:93], v[158:161], v[224:227], v[90:93]
	v_mfma_f32_16x16x32_bf16 v[78:81], v[150:153], v[232:235], v[78:81]
	v_mfma_f32_16x16x32_bf16 v[74:77], v[158:161], v[232:235], v[74:77]
	s_setprio 0
	s_setprio 1
	v_mfma_f32_16x16x32_bf16 v[118:121], v[174:177], v[200:203], v[118:121]
	v_mfma_f32_16x16x32_bf16 v[114:117], v[182:185], v[200:203], v[114:117]
	v_mfma_f32_16x16x32_bf16 v[102:105], v[174:177], v[212:215], v[102:105]
	v_mfma_f32_16x16x32_bf16 v[98:101], v[182:185], v[212:215], v[98:101]
	v_mfma_f32_16x16x32_bf16 v[86:89], v[174:177], v[220:223], v[86:89]
	v_mfma_f32_16x16x32_bf16 v[82:85], v[182:185], v[220:223], v[82:85]
	v_mfma_f32_16x16x32_bf16 v[70:73], v[174:177], v[228:231], v[70:73]
	v_mfma_f32_16x16x32_bf16 v[66:69], v[182:185], v[228:231], v[66:69]
	v_mfma_f32_16x16x32_bf16 v[118:121], v[178:181], v[208:211], v[118:121]
	v_mfma_f32_16x16x32_bf16 v[114:117], v[186:189], v[208:211], v[114:117]
	v_mfma_f32_16x16x32_bf16 v[102:105], v[178:181], v[216:219], v[102:105]
	v_mfma_f32_16x16x32_bf16 v[98:101], v[186:189], v[216:219], v[98:101]
	s_barrier
; #define PG8_STAGE(bufoff, gbase, voff) do { _Pragma("unroll") for (int _i = 0; _i < 2; ++_i) \
;         __builtin_amdgcn_global_load_lds((const unsigned*)((const char*)(gbase) + (voff)[_i]), (PG8_LAS unsigned*)(lds + (bufoff) + ldsw + _i * 8192), 16, 0, 0); } while (0)
; #define PG8_STAGEA(bufoff, gbase, voff) do { _Pragma("unroll") for (int _i = 0; _i < 2; ++_i) \
;         __builtin_amdgcn_global_load_lds((const unsigned*)((const char*)(gbase) + (voff)[_i]), (PG8_LAS unsigned*)(lds + (bufoff) + ldsw + _i * 8192), 16, 0, A_AUX); } while (0)
; #define PG8_LDA(dst, b, h) do { _Pragma("unroll") for (int m = 0; m < 4; ++m) _Pragma("unroll") for (int k = 0; k < 2; ++k) dst[m][k] = *(const PG8_LAS bf16x8*)(lds + PG8_SA(b, h) + aoff + m * 2048 + k * 1024); } while (0)
; #define PG8_WAIT_V(n) asm volatile("s_waitcnt vmcnt(" #n ")" ::: "memory")
; #define PG8_BAR __builtin_amdgcn_s_barrier()
;     ...
;         for (int t = 0; t < nt; t += 2) {
;             const bool last = (t == nt - 2);
;             const char* a1 = cA + (size_t)(t + 1) * kstep;
;             const char* a2 = last ? nA : cA + (size_t)(t + 2) * kstep; const char* b2 = last ? nB : cB + (size_t)(t + 2) * kstep;
;             const char* a3 = a2 + kstep; const char* b3 = b2 + kstep;
;             if (last && has_next) S.a_ready(nxt);
;             if constexpr (SP2) {
;             PG8_LDB(B0, 0, 0); PG8_LDB(B1, 0, 1); PG8_SCHED; PG8_LDA(At, 0, 0); PG8_STAGEA(PG8_SA(1, 1), a1 + hstep, voffA);
;             PG8_WAIT_V(8); PG8_WAIT_L(0); PG8_BAR; PG8_MMA(0, 0, At, B0); PG8_MMA(0, 1, At, B1); PG8_BAR; PG8_SCHED;
;             PG8_LDA(At, 0, 1); PG8_STAGE(PG8_SB(0, 0), b2, voffB); PG8_STAGE(PG8_SB(0, 1), b2 + hstep, voffB); PG8_STAGEA(PG8_SA(0, 0), a2, voffA);
;             PG8_WAIT_V(8); PG8_WAIT_L(0); PG8_BAR; PG8_MMA(1, 0, At, B0); PG8_MMA(1, 1, At, B1); PG8_BAR; PG8_SCHED;
;             PG8_LDB(B0, 1, 0); PG8_LDB(B1, 1, 1); PG8_SCHED; PG8_LDA(At, 1, 0); PG8_STAGEA(PG8_SA(0, 1), a2 + hstep, voffA);
;             PG8_WAIT_V(8); PG8_WAIT_L(0); PG8_BAR; PG8_MMA(0, 0, At, B0); PG8_MMA(0, 1, At, B1); PG8_BAR; PG8_SCHED;
;             PG8_LDA(At, 1, 1); PG8_STAGE(PG8_SB(1, 0), b3, voffB); PG8_STAGE(PG8_SB(1, 1), b3 + hstep, voffB); PG8_STAGEA(PG8_SA(1, 0), a3, voffA);
;             PG8_WAIT_V(8); PG8_WAIT_L(0); PG8_BAR; PG8_MMA(1, 0, At, B0); PG8_MMA(1, 1, At, B1); PG8_BAR; PG8_SCHED;
	v_mfma_f32_16x16x32_bf16 v[86:89], v[178:181], v[224:227], v[86:89]
	v_mfma_f32_16x16x32_bf16 v[82:85], v[186:189], v[224:227], v[82:85]
	v_mfma_f32_16x16x32_bf16 v[70:73], v[178:181], v[232:235], v[70:73]
	v_mfma_f32_16x16x32_bf16 v[66:69], v[186:189], v[232:235], v[66:69]
	s_setprio 0
	s_nop 0
	s_add_i32 s54, s70, s57
	v_lshl_add_u64 v[140:141], v[140:141], 0, s[8:9]
	s_mov_b32 m0, s54
	ds_read_b128 v[200:203], v145 offset:49152
	ds_read_b128 v[208:211], v145 offset:50176
	ds_read_b128 v[212:215], v145 offset:51200
	ds_read_b128 v[216:219], v145 offset:52224
	ds_read_b128 v[220:223], v145 offset:53248
	ds_read_b128 v[224:227], v145 offset:54272
	ds_read_b128 v[228:231], v145 offset:55296
	ds_read_b128 v[232:235], v145 offset:56320
	global_load_lds_dwordx4 v[140:141], off
	s_add_i32 m0, s54, 0x2000
	s_add_u32 s52, s52, 0x40080
	v_lshl_add_u64 v[140:141], v[190:191], 0, s[8:9]
	s_addc_u32 s53, s53, 0
	s_add_i32 s54, s71, s57
	global_load_lds_dwordx4 v[140:141], off
	v_lshl_add_u64 v[140:141], s[52:53], 0, v[0:1]
	s_mov_b32 m0, s54
	s_nop 0
	global_load_lds_dwordx4 v[140:141], off
	v_lshl_add_u64 v[140:141], s[52:53], 0, v[130:131]
	s_add_i32 m0, s54, 0x2000
	s_nop 0
	global_load_lds_dwordx4 v[140:141], off
	v_lshl_add_u64 v[140:141], v[236:237], 0, s[8:9]
	s_mov_b32 m0, s62
	s_nop 0
	global_load_lds_dwordx4 v[140:141], off
	v_lshl_add_u64 v[140:141], v[238:239], 0, s[8:9]
	s_mov_b32 m0, s63
	s_nop 0
	global_load_lds_dwordx4 v[140:141], off
	s_waitcnt vmcnt(8)
	s_waitcnt lgkmcnt(0)
	s_barrier
	s_setprio 1
	s_waitcnt lgkmcnt(0)
	v_mfma_f32_16x16x32_bf16 v[62:65], v[146:149], v[200:203], v[62:65]
	v_mfma_f32_16x16x32_bf16 v[58:61], v[154:157], v[200:203], v[58:61]
	v_mfma_f32_16x16x32_bf16 v[46:49], v[146:149], v[212:215], v[46:49]
	v_mfma_f32_16x16x32_bf16 v[42:45], v[154:157], v[212:215], v[42:45]
	v_mfma_f32_16x16x32_bf16 v[30:33], v[146:149], v[220:223], v[30:33]
	v_mfma_f32_16x16x32_bf16 v[26:29], v[154:157], v[220:223], v[26:29]
	v_mfma_f32_16x16x32_bf16 v[14:17], v[146:149], v[228:231], v[14:17]
	v_mfma_f32_16x16x32_bf16 v[10:13], v[154:157], v[228:231], v[10:13]
	v_mfma_f32_16x16x32_bf16 v[62:65], v[150:153], v[208:211], v[62:65]
	v_mfma_f32_16x16x32_bf16 v[58:61], v[158:161], v[208:211], v[58:61]
	v_mfma_f32_16x16x32_bf16 v[46:49], v[150:153], v[216:219], v[46:49]
	v_mfma_f32_16x16x32_bf16 v[42:45], v[158:161], v[216:219], v[42:45]
	v_mfma_f32_16x16x32_bf16 v[30:33], v[150:153], v[224:227], v[30:33]
	v_mfma_f32_16x16x32_bf16 v[26:29], v[158:161], v[224:227], v[26:29]
	v_mfma_f32_16x16x32_bf16 v[14:17], v[150:153], v[232:235], v[14:17]
	v_mfma_f32_16x16x32_bf16 v[10:13], v[158:161], v[232:235], v[10:13]
	s_setprio 0
	s_setprio 1
	v_mfma_f32_16x16x32_bf16 v[54:57], v[174:177], v[200:203], v[54:57]
	v_mfma_f32_16x16x32_bf16 v[50:53], v[182:185], v[200:203], v[50:53]
	v_mfma_f32_16x16x32_bf16 v[38:41], v[174:177], v[212:215], v[38:41]
	v_mfma_f32_16x16x32_bf16 v[34:37], v[182:185], v[212:215], v[34:37]
	v_mfma_f32_16x16x32_bf16 v[22:25], v[174:177], v[220:223], v[22:25]
	v_mfma_f32_16x16x32_bf16 v[18:21], v[182:185], v[220:223], v[18:21]
	v_mfma_f32_16x16x32_bf16 v[6:9], v[174:177], v[228:231], v[6:9]
	v_mfma_f32_16x16x32_bf16 v[2:5], v[182:185], v[228:231], v[2:5]
	v_mfma_f32_16x16x32_bf16 v[54:57], v[178:181], v[208:211], v[54:57]
	v_mfma_f32_16x16x32_bf16 v[50:53], v[186:189], v[208:211], v[50:53]
	v_mfma_f32_16x16x32_bf16 v[38:41], v[178:181], v[216:219], v[38:41]
	v_mfma_f32_16x16x32_bf16 v[34:37], v[186:189], v[216:219], v[34:37]
	s_barrier
	v_mfma_f32_16x16x32_bf16 v[22:25], v[178:181], v[224:227], v[22:25]
	v_mfma_f32_16x16x32_bf16 v[18:21], v[186:189], v[224:227], v[18:21]
	v_mfma_f32_16x16x32_bf16 v[6:9], v[178:181], v[232:235], v[6:9]
	v_mfma_f32_16x16x32_bf16 v[2:5], v[186:189], v[232:235], v[2:5]
	s_setprio 0
	s_nop 0
	s_add_i32 vcc_lo, vcc_lo, 2
	s_add_u32 s50, s50, 0x100
	s_addc_u32 s51, s51, 0
	s_add_u32 s73, s73, 0x100
	s_addc_u32 s76, s76, 0
	s_cmp_gt_u32 vcc_lo, 13
	s_cbranch_scc0 .LBB0_580
	s_and_b64 vcc, exec, s[36:37]
	s_cbranch_vccz .LBB0_583
	s_barrier

; #define PG8_STAGE(bufoff, gbase, voff) do { _Pragma("unroll") for (int _i = 0; _i < 2; ++_i) \
;         __builtin_amdgcn_global_load_lds((const unsigned*)((const char*)(gbase) + (voff)[_i]), (PG8_LAS unsigned*)(lds + (bufoff) + ldsw + _i * 8192), 16, 0, 0); } while (0)
; #define PG8_STAGEA(bufoff, gbase, voff) do { _Pragma("unroll") for (int _i = 0; _i < 2; ++_i) \
;         __builtin_amdgcn_global_load_lds((const unsigned*)((const char*)(gbase) + (voff)[_i]), (PG8_LAS unsigned*)(lds + (bufoff) + ldsw + _i * 8192), 16, 0, A_AUX); } while (0)
; #define PG8_LDA(dst, b, h) do { _Pragma("unroll") for (int m = 0; m < 4; ++m) _Pragma("unroll") for (int k = 0; k < 2; ++k) dst[m][k] = *(const PG8_LAS bf16x8*)(lds + PG8_SA(b, h) + aoff + m * 2048 + k * 1024); } while (0)
; #define PG8_WAIT_V(n) asm volatile("s_waitcnt vmcnt(" #n ")" ::: "memory")
; #define PG8_BAR __builtin_amdgcn_s_barrier()
;     ...
;         for (int t = 0; t < nt; t += 2) {
;             const bool last = (t == nt - 2);
;             const char* a1 = cA + (size_t)(t + 1) * kstep;
;             const char* a2 = last ? nA : cA + (size_t)(t + 2) * kstep; const char* b2 = last ? nB : cB + (size_t)(t + 2) * kstep;
;             const char* a3 = a2 + kstep; const char* b3 = b2 + kstep;
;             if (last && has_next) S.a_ready(nxt);
;             if constexpr (SP2) {
;             PG8_LDB(B0, 0, 0); PG8_LDB(B1, 0, 1); PG8_SCHED; PG8_LDA(At, 0, 0); PG8_STAGEA(PG8_SA(1, 1), a1 + hstep, voffA);
;             PG8_WAIT_V(8); PG8_WAIT_L(0); PG8_BAR; PG8_MMA(0, 0, At, B0); PG8_MMA(0, 1, At, B1); PG8_BAR; PG8_SCHED;
;             PG8_LDA(At, 0, 1); PG8_STAGE(PG8_SB(0, 0), b2, voffB); PG8_STAGE(PG8_SB(0, 1), b2 + hstep, voffB); PG8_STAGEA(PG8_SA(0, 0), a2, voffA);
;             PG8_WAIT_V(8); PG8_WAIT_L(0); PG8_BAR; PG8_MMA(1, 0, At, B0); PG8_MMA(1, 1, At, B1); PG8_BAR; PG8_SCHED;
;             PG8_LDB(B0, 1, 0); PG8_LDB(B1, 1, 1); PG8_SCHED; PG8_LDA(At, 1, 0); PG8_STAGEA(PG8_SA(0, 1), a2 + hstep, voffA);
;             PG8_WAIT_V(8); PG8_WAIT_L(0); PG8_BAR; PG8_MMA(0, 0, At, B0); PG8_MMA(0, 1, At, B1); PG8_BAR; PG8_SCHED;
;             PG8_LDA(At, 1, 1); PG8_STAGE(PG8_SB(1, 0), b3, voffB); PG8_STAGE(PG8_SB(1, 1), b3 + hstep, voffB); PG8_STAGEA(PG8_SA(1, 0), a3, voffA);
;             PG8_WAIT_V(8); PG8_WAIT_L(0); PG8_BAR; PG8_MMA(1, 0, At, B0); PG8_MMA(1, 1, At, B1); PG8_BAR; PG8_SCHED;
.LBB0_656:
	s_add_u32 s48, s46, 0x100
	s_addc_u32 s49, s47, 0
	s_add_i32 s70, 0, 0x10000
	s_cmp_eq_u32 s73, 40
	s_cselect_b32 s53, s1, s49
	s_cselect_b32 s52, s0, s48
	v_add_u32_e32 v140, s70, v143
	s_cselect_b32 s51, s45, s17
	s_cselect_b32 s50, s44, s16
	s_add_i32 s71, 0, 0x14000
	ds_read_b128 v[146:149], v140
	ds_read_b128 v[150:153], v140 offset:1024
	ds_read_b128 v[154:157], v140 offset:2048
	ds_read_b128 v[158:161], v140 offset:3072
	v_add_u32_e32 v140, s71, v143
	ds_read_b128 v[174:177], v140
	ds_read_b128 v[178:181], v140 offset:1024
	ds_read_b128 v[182:185], v140 offset:2048
	ds_read_b128 v[186:189], v140 offset:3072
	v_lshl_add_u64 v[140:141], s[46:47], 0, v[136:137]
	s_add_i32 m0, s56, 0xc000
	ds_read_b128 v[200:203], v145
	ds_read_b128 v[208:211], v145 offset:1024
	ds_read_b128 v[212:215], v145 offset:2048
	ds_read_b128 v[216:219], v145 offset:3072
	ds_read_b128 v[220:223], v145 offset:4096
	ds_read_b128 v[224:227], v145 offset:5120
	ds_read_b128 v[228:231], v145 offset:6144
	ds_read_b128 v[232:235], v145 offset:7168
	global_load_lds_dwordx4 v[140:141], off
	v_lshl_add_u64 v[140:141], s[46:47], 0, v[138:139]
	s_add_i32 m0, s56, 0xe000
	s_nop 0
	global_load_lds_dwordx4 v[140:141], off
	s_waitcnt vmcnt(8)
	s_waitcnt lgkmcnt(0)
	s_barrier
	s_setprio 1
	s_waitcnt lgkmcnt(0)
	v_mfma_f32_16x16x32_bf16 v[126:129], v[146:149], v[200:203], v[126:129]
	v_mfma_f32_16x16x32_bf16 v[122:125], v[154:157], v[200:203], v[122:125]
	v_mfma_f32_16x16x32_bf16 v[114:117], v[146:149], v[212:215], v[114:117]
	v_mfma_f32_16x16x32_bf16 v[106:109], v[154:157], v[212:215], v[106:109]
	v_mfma_f32_16x16x32_bf16 v[98:101], v[146:149], v[220:223], v[98:101]
	v_mfma_f32_16x16x32_bf16 v[90:93], v[154:157], v[220:223], v[90:93]
	v_mfma_f32_16x16x32_bf16 v[82:85], v[146:149], v[228:231], v[82:85]
	v_mfma_f32_16x16x32_bf16 v[74:77], v[154:157], v[228:231], v[74:77]
	v_mfma_f32_16x16x32_bf16 v[126:129], v[150:153], v[208:211], v[126:129]
	v_mfma_f32_16x16x32_bf16 v[122:125], v[158:161], v[208:211], v[122:125]
	v_mfma_f32_16x16x32_bf16 v[114:117], v[150:153], v[216:219], v[114:117]
	v_mfma_f32_16x16x32_bf16 v[106:109], v[158:161], v[216:219], v[106:109]
	v_mfma_f32_16x16x32_bf16 v[98:101], v[150:153], v[224:227], v[98:101]
	v_mfma_f32_16x16x32_bf16 v[90:93], v[158:161], v[224:227], v[90:93]
	v_mfma_f32_16x16x32_bf16 v[82:85], v[150:153], v[232:235], v[82:85]
	v_mfma_f32_16x16x32_bf16 v[74:77], v[158:161], v[232:235], v[74:77]
	s_setprio 0
	s_setprio 1
	v_mfma_f32_16x16x32_bf16 v[118:121], v[174:177], v[200:203], v[118:121]
	v_mfma_f32_16x16x32_bf16 v[110:113], v[182:185], v[200:203], v[110:113]
	v_mfma_f32_16x16x32_bf16 v[102:105], v[174:177], v[212:215], v[102:105]
	v_mfma_f32_16x16x32_bf16 v[94:97], v[182:185], v[212:215], v[94:97]
	v_mfma_f32_16x16x32_bf16 v[86:89], v[174:177], v[220:223], v[86:89]
	v_mfma_f32_16x16x32_bf16 v[78:81], v[182:185], v[220:223], v[78:81]
	v_mfma_f32_16x16x32_bf16 v[70:73], v[174:177], v[228:231], v[70:73]
	v_mfma_f32_16x16x32_bf16 v[66:69], v[182:185], v[228:231], v[66:69]
	v_mfma_f32_16x16x32_bf16 v[118:121], v[178:181], v[208:211], v[118:121]
	v_mfma_f32_16x16x32_bf16 v[110:113], v[186:189], v[208:211], v[110:113]
	v_mfma_f32_16x16x32_bf16 v[102:105], v[178:181], v[216:219], v[102:105]
	v_mfma_f32_16x16x32_bf16 v[94:97], v[186:189], v[216:219], v[94:97]
	s_barrier
	v_mfma_f32_16x16x32_bf16 v[86:89], v[178:181], v[224:227], v[86:89]
	v_mfma_f32_16x16x32_bf16 v[78:81], v[186:189], v[224:227], v[78:81]
	v_mfma_f32_16x16x32_bf16 v[70:73], v[178:181], v[232:235], v[70:73]
	v_mfma_f32_16x16x32_bf16 v[66:69], v[186:189], v[232:235], v[66:69]
	s_setprio 0
	s_nop 0
	s_add_i32 s46, s70, s55
	v_lshl_add_u64 v[140:141], s[50:51], 0, v[0:1]
	s_mov_b32 m0, s46
	ds_read_b128 v[200:203], v145 offset:16384
	ds_read_b128 v[208:211], v145 offset:17408
	ds_read_b128 v[212:215], v145 offset:18432
	ds_read_b128 v[216:219], v145 offset:19456
	ds_read_b128 v[220:223], v145 offset:20480
	ds_read_b128 v[224:227], v145 offset:21504
	ds_read_b128 v[228:231], v145 offset:22528
	ds_read_b128 v[232:235], v145 offset:23552
	global_load_lds_dwordx4 v[140:141], off
	s_add_i32 m0, s46, 0x2000
	s_add_u32 s46, s50, 0xb0000
	v_lshl_add_u64 v[190:191], s[50:51], 0, v[130:131]
	s_addc_u32 s47, s51, 0
	s_add_i32 s70, s71, s55
	global_load_lds_dwordx4 v[190:191], off
	v_lshl_add_u64 v[236:237], s[46:47], 0, v[0:1]
	s_mov_b32 m0, s70
	v_lshl_add_u64 v[238:239], s[52:53], 0, v[132:133]
	global_load_lds_dwordx4 v[236:237], off
	v_lshl_add_u64 v[236:237], s[46:47], 0, v[130:131]
	s_add_i32 m0, s70, 0x2000
	s_nop 0
	global_load_lds_dwordx4 v[236:237], off
	v_lshl_add_u64 v[236:237], s[52:53], 0, v[134:135]
	s_mov_b32 m0, s56
	s_nop 0
	global_load_lds_dwordx4 v[236:237], off
	s_mov_b32 m0, s57
	s_nop 0
	global_load_lds_dwordx4 v[238:239], off
	s_waitcnt vmcnt(8)
	s_waitcnt lgkmcnt(0)
	s_barrier
; #define PG8_STAGE(bufoff, gbase, voff) do { _Pragma("unroll") for (int _i = 0; _i < 2; ++_i) \
;         __builtin_amdgcn_global_load_lds((const unsigned*)((const char*)(gbase) + (voff)[_i]), (PG8_LAS unsigned*)(lds + (bufoff) + ldsw + _i * 8192), 16, 0, 0); } while (0)
; #define PG8_STAGEA(bufoff, gbase, voff) do { _Pragma("unroll") for (int _i = 0; _i < 2; ++_i) \
;         __builtin_amdgcn_global_load_lds((const unsigned*)((const char*)(gbase) + (voff)[_i]), (PG8_LAS unsigned*)(lds + (bufoff) + ldsw + _i * 8192), 16, 0, A_AUX); } while (0)
; #define PG8_LDA(dst, b, h) do { _Pragma("unroll") for (int m = 0; m < 4; ++m) _Pragma("unroll") for (int k = 0; k < 2; ++k) dst[m][k] = *(const PG8_LAS bf16x8*)(lds + PG8_SA(b, h) + aoff + m * 2048 + k * 1024); } while (0)
; #define PG8_WAIT_V(n) asm volatile("s_waitcnt vmcnt(" #n ")" ::: "memory")
; #define PG8_BAR __builtin_amdgcn_s_barrier()
;     ...
;         for (int t = 0; t < nt; t += 2) {
;             const bool last = (t == nt - 2);
;             const char* a1 = cA + (size_t)(t + 1) * kstep;
;             const char* a2 = last ? nA : cA + (size_t)(t + 2) * kstep; const char* b2 = last ? nB : cB + (size_t)(t + 2) * kstep;
;             const char* a3 = a2 + kstep; const char* b3 = b2 + kstep;
;             if (last && has_next) S.a_ready(nxt);
;             if constexpr (SP2) {
;             PG8_LDB(B0, 0, 0); PG8_LDB(B1, 0, 1); PG8_SCHED; PG8_LDA(At, 0, 0); PG8_STAGEA(PG8_SA(1, 1), a1 + hstep, voffA);
;             PG8_WAIT_V(8); PG8_WAIT_L(0); PG8_BAR; PG8_MMA(0, 0, At, B0); PG8_MMA(0, 1, At, B1); PG8_BAR; PG8_SCHED;
;             PG8_LDA(At, 0, 1); PG8_STAGE(PG8_SB(0, 0), b2, voffB); PG8_STAGE(PG8_SB(0, 1), b2 + hstep, voffB); PG8_STAGEA(PG8_SA(0, 0), a2, voffA);
;             PG8_WAIT_V(8); PG8_WAIT_L(0); PG8_BAR; PG8_MMA(1, 0, At, B0); PG8_MMA(1, 1, At, B1); PG8_BAR; PG8_SCHED;
;             PG8_LDB(B0, 1, 0); PG8_LDB(B1, 1, 1); PG8_SCHED; PG8_LDA(At, 1, 0); PG8_STAGEA(PG8_SA(0, 1), a2 + hstep, voffA);
;             PG8_WAIT_V(8); PG8_WAIT_L(0); PG8_BAR; PG8_MMA(0, 0, At, B0); PG8_MMA(0, 1, At, B1); PG8_BAR; PG8_SCHED;
;             PG8_LDA(At, 1, 1); PG8_STAGE(PG8_SB(1, 0), b3, voffB); PG8_STAGE(PG8_SB(1, 1), b3 + hstep, voffB); PG8_STAGEA(PG8_SA(1, 0), a3, voffA);
;             PG8_WAIT_V(8); PG8_WAIT_L(0); PG8_BAR; PG8_MMA(1, 0, At, B0); PG8_MMA(1, 1, At, B1); PG8_BAR; PG8_SCHED;
	s_setprio 1
	s_waitcnt lgkmcnt(0)
	v_mfma_f32_16x16x32_bf16 v[62:65], v[146:149], v[200:203], v[62:65]
	v_mfma_f32_16x16x32_bf16 v[58:61], v[154:157], v[200:203], v[58:61]
	v_mfma_f32_16x16x32_bf16 v[50:53], v[146:149], v[212:215], v[50:53]
	v_mfma_f32_16x16x32_bf16 v[42:45], v[154:157], v[212:215], v[42:45]
	v_mfma_f32_16x16x32_bf16 v[34:37], v[146:149], v[220:223], v[34:37]
	v_mfma_f32_16x16x32_bf16 v[26:29], v[154:157], v[220:223], v[26:29]
	v_mfma_f32_16x16x32_bf16 v[18:21], v[146:149], v[228:231], v[18:21]
	v_mfma_f32_16x16x32_bf16 v[10:13], v[154:157], v[228:231], v[10:13]
	v_mfma_f32_16x16x32_bf16 v[62:65], v[150:153], v[208:211], v[62:65]
	v_mfma_f32_16x16x32_bf16 v[58:61], v[158:161], v[208:211], v[58:61]
	v_mfma_f32_16x16x32_bf16 v[50:53], v[150:153], v[216:219], v[50:53]
	v_mfma_f32_16x16x32_bf16 v[42:45], v[158:161], v[216:219], v[42:45]
	v_mfma_f32_16x16x32_bf16 v[34:37], v[150:153], v[224:227], v[34:37]
	v_mfma_f32_16x16x32_bf16 v[26:29], v[158:161], v[224:227], v[26:29]
	v_mfma_f32_16x16x32_bf16 v[18:21], v[150:153], v[232:235], v[18:21]
	v_mfma_f32_16x16x32_bf16 v[10:13], v[158:161], v[232:235], v[10:13]
	s_setprio 0
	s_setprio 1
	v_mfma_f32_16x16x32_bf16 v[54:57], v[174:177], v[200:203], v[54:57]
	v_mfma_f32_16x16x32_bf16 v[46:49], v[182:185], v[200:203], v[46:49]
	v_mfma_f32_16x16x32_bf16 v[38:41], v[174:177], v[212:215], v[38:41]
	v_mfma_f32_16x16x32_bf16 v[30:33], v[182:185], v[212:215], v[30:33]
	v_mfma_f32_16x16x32_bf16 v[22:25], v[174:177], v[220:223], v[22:25]
	v_mfma_f32_16x16x32_bf16 v[14:17], v[182:185], v[220:223], v[14:17]
	v_mfma_f32_16x16x32_bf16 v[6:9], v[174:177], v[228:231], v[6:9]
	v_mfma_f32_16x16x32_bf16 v[2:5], v[182:185], v[228:231], v[2:5]
	v_mfma_f32_16x16x32_bf16 v[54:57], v[178:181], v[208:211], v[54:57]
	v_mfma_f32_16x16x32_bf16 v[46:49], v[186:189], v[208:211], v[46:49]
	v_mfma_f32_16x16x32_bf16 v[38:41], v[178:181], v[216:219], v[38:41]
	v_mfma_f32_16x16x32_bf16 v[30:33], v[186:189], v[216:219], v[30:33]
	s_barrier
	v_mfma_f32_16x16x32_bf16 v[22:25], v[178:181], v[224:227], v[22:25]
	v_mfma_f32_16x16x32_bf16 v[14:17], v[186:189], v[224:227], v[14:17]
	v_mfma_f32_16x16x32_bf16 v[6:9], v[178:181], v[232:235], v[6:9]
	v_mfma_f32_16x16x32_bf16 v[2:5], v[186:189], v[232:235], v[2:5]
	s_setprio 0
	s_nop 0
	s_add_i32 s70, 0, 0x18000
	s_add_i32 s71, 0, 0x1c000
	v_add_u32_e32 v158, s70, v143
	v_add_u32_e32 v186, s71, v143
	ds_read_b128 v[146:149], v158
	ds_read_b128 v[150:153], v158 offset:1024
	ds_read_b128 v[154:157], v158 offset:2048
	ds_read_b128 v[158:161], v158 offset:3072
	ds_read_b128 v[174:177], v186
	ds_read_b128 v[178:181], v186 offset:1024
	ds_read_b128 v[182:185], v186 offset:2048
	ds_read_b128 v[186:189], v186 offset:3072
	s_add_u32 s46, s52, 0xb0000
	s_addc_u32 s47, s53, 0
	s_mov_b32 m0, s58
	v_lshl_add_u64 v[240:241], s[46:47], 0, v[134:135]
	ds_read_b128 v[200:203], v145 offset:32768
	ds_read_b128 v[208:211], v145 offset:33792
	ds_read_b128 v[212:215], v145 offset:34816
	ds_read_b128 v[216:219], v145 offset:35840
	ds_read_b128 v[220:223], v145 offset:36864
	ds_read_b128 v[224:227], v145 offset:37888
	ds_read_b128 v[228:231], v145 offset:38912
	ds_read_b128 v[232:235], v145 offset:39936
	global_load_lds_dwordx4 v[240:241], off
	v_lshl_add_u64 v[240:241], s[46:47], 0, v[132:133]
	s_mov_b32 m0, s59
	s_nop 0
	global_load_lds_dwordx4 v[240:241], off
	s_waitcnt vmcnt(8)
	s_waitcnt lgkmcnt(0)
	s_barrier
	s_setprio 1
	s_waitcnt lgkmcnt(0)
	v_mfma_f32_16x16x32_bf16 v[126:129], v[146:149], v[200:203], v[126:129]
	v_mfma_f32_16x16x32_bf16 v[122:125], v[154:157], v[200:203], v[122:125]
	v_mfma_f32_16x16x32_bf16 v[114:117], v[146:149], v[212:215], v[114:117]
	v_mfma_f32_16x16x32_bf16 v[106:109], v[154:157], v[212:215], v[106:109]
	v_mfma_f32_16x16x32_bf16 v[98:101], v[146:149], v[220:223], v[98:101]
	v_mfma_f32_16x16x32_bf16 v[90:93], v[154:157], v[220:223], v[90:93]
	v_mfma_f32_16x16x32_bf16 v[82:85], v[146:149], v[228:231], v[82:85]
	v_mfma_f32_16x16x32_bf16 v[74:77], v[154:157], v[228:231], v[74:77]
	v_mfma_f32_16x16x32_bf16 v[126:129], v[150:153], v[208:211], v[126:129]
	v_mfma_f32_16x16x32_bf16 v[122:125], v[158:161], v[208:211], v[122:125]
	v_mfma_f32_16x16x32_bf16 v[114:117], v[150:153], v[216:219], v[114:117]
	v_mfma_f32_16x16x32_bf16 v[106:109], v[158:161], v[216:219], v[106:109]
	v_mfma_f32_16x16x32_bf16 v[98:101], v[150:153], v[224:227], v[98:101]
	v_mfma_f32_16x16x32_bf16 v[90:93], v[158:161], v[224:227], v[90:93]
	v_mfma_f32_16x16x32_bf16 v[82:85], v[150:153], v[232:235], v[82:85]
	v_mfma_f32_16x16x32_bf16 v[74:77], v[158:161], v[232:235], v[74:77]
	s_setprio 0
	s_setprio 1
	v_mfma_f32_16x16x32_bf16 v[118:121], v[174:177], v[200:203], v[118:121]
	v_mfma_f32_16x16x32_bf16 v[110:113], v[182:185], v[200:203], v[110:113]
	v_mfma_f32_16x16x32_bf16 v[102:105], v[174:177], v[212:215], v[102:105]
	v_mfma_f32_16x16x32_bf16 v[94:97], v[182:185], v[212:215], v[94:97]
	v_mfma_f32_16x16x32_bf16 v[86:89], v[174:177], v[220:223], v[86:89]
	v_mfma_f32_16x16x32_bf16 v[78:81], v[182:185], v[220:223], v[78:81]
	v_mfma_f32_16x16x32_bf16 v[70:73], v[174:177], v[228:231], v[70:73]
	v_mfma_f32_16x16x32_bf16 v[66:69], v[182:185], v[228:231], v[66:69]
	v_mfma_f32_16x16x32_bf16 v[118:121], v[178:181], v[208:211], v[118:121]
	v_mfma_f32_16x16x32_bf16 v[110:113], v[186:189], v[208:211], v[110:113]
	v_mfma_f32_16x16x32_bf16 v[102:105], v[178:181], v[216:219], v[102:105]
	v_mfma_f32_16x16x32_bf16 v[94:97], v[186:189], v[216:219], v[94:97]
	s_barrier
; #define PG8_STAGE(bufoff, gbase, voff) do { _Pragma("unroll") for (int _i = 0; _i < 2; ++_i) \
;         __builtin_amdgcn_global_load_lds((const unsigned*)((const char*)(gbase) + (voff)[_i]), (PG8_LAS unsigned*)(lds + (bufoff) + ldsw + _i * 8192), 16, 0, 0); } while (0)
; #define PG8_STAGEA(bufoff, gbase, voff) do { _Pragma("unroll") for (int _i = 0; _i < 2; ++_i) \
;         __builtin_amdgcn_global_load_lds((const unsigned*)((const char*)(gbase) + (voff)[_i]), (PG8_LAS unsigned*)(lds + (bufoff) + ldsw + _i * 8192), 16, 0, A_AUX); } while (0)
; #define PG8_LDA(dst, b, h) do { _Pragma("unroll") for (int m = 0; m < 4; ++m) _Pragma("unroll") for (int k = 0; k < 2; ++k) dst[m][k] = *(const PG8_LAS bf16x8*)(lds + PG8_SA(b, h) + aoff + m * 2048 + k * 1024); } while (0)
; #define PG8_WAIT_V(n) asm volatile("s_waitcnt vmcnt(" #n ")" ::: "memory")
; #define PG8_BAR __builtin_amdgcn_s_barrier()
;     ...
;         for (int t = 0; t < nt; t += 2) {
;             const bool last = (t == nt - 2);
;             const char* a1 = cA + (size_t)(t + 1) * kstep;
;             const char* a2 = last ? nA : cA + (size_t)(t + 2) * kstep; const char* b2 = last ? nB : cB + (size_t)(t + 2) * kstep;
;             const char* a3 = a2 + kstep; const char* b3 = b2 + kstep;
;             if (last && has_next) S.a_ready(nxt);
;             if constexpr (SP2) {
;             PG8_LDB(B0, 0, 0); PG8_LDB(B1, 0, 1); PG8_SCHED; PG8_LDA(At, 0, 0); PG8_STAGEA(PG8_SA(1, 1), a1 + hstep, voffA);
;             PG8_WAIT_V(8); PG8_WAIT_L(0); PG8_BAR; PG8_MMA(0, 0, At, B0); PG8_MMA(0, 1, At, B1); PG8_BAR; PG8_SCHED;
;             PG8_LDA(At, 0, 1); PG8_STAGE(PG8_SB(0, 0), b2, voffB); PG8_STAGE(PG8_SB(0, 1), b2 + hstep, voffB); PG8_STAGEA(PG8_SA(0, 0), a2, voffA);
;             PG8_WAIT_V(8); PG8_WAIT_L(0); PG8_BAR; PG8_MMA(1, 0, At, B0); PG8_MMA(1, 1, At, B1); PG8_BAR; PG8_SCHED;
;             PG8_LDB(B0, 1, 0); PG8_LDB(B1, 1, 1); PG8_SCHED; PG8_LDA(At, 1, 0); PG8_STAGEA(PG8_SA(0, 1), a2 + hstep, voffA);
;             PG8_WAIT_V(8); PG8_WAIT_L(0); PG8_BAR; PG8_MMA(0, 0, At, B0); PG8_MMA(0, 1, At, B1); PG8_BAR; PG8_SCHED;
;             PG8_LDA(At, 1, 1); PG8_STAGE(PG8_SB(1, 0), b3, voffB); PG8_STAGE(PG8_SB(1, 1), b3 + hstep, voffB); PG8_STAGEA(PG8_SA(1, 0), a3, voffA);
;             PG8_WAIT_V(8); PG8_WAIT_L(0); PG8_BAR; PG8_MMA(1, 0, At, B0); PG8_MMA(1, 1, At, B1); PG8_BAR; PG8_SCHED;
	v_mfma_f32_16x16x32_bf16 v[86:89], v[178:181], v[224:227], v[86:89]
	v_mfma_f32_16x16x32_bf16 v[78:81], v[186:189], v[224:227], v[78:81]
	v_mfma_f32_16x16x32_bf16 v[70:73], v[178:181], v[232:235], v[70:73]
	v_mfma_f32_16x16x32_bf16 v[66:69], v[186:189], v[232:235], v[66:69]
	s_setprio 0
	s_nop 0
	s_add_i32 s46, s70, s55
	v_lshl_add_u64 v[140:141], v[140:141], 0, s[8:9]
	s_mov_b32 m0, s46
	ds_read_b128 v[200:203], v145 offset:49152
	ds_read_b128 v[208:211], v145 offset:50176
	ds_read_b128 v[212:215], v145 offset:51200
	ds_read_b128 v[216:219], v145 offset:52224
	ds_read_b128 v[220:223], v145 offset:53248
	ds_read_b128 v[224:227], v145 offset:54272
	ds_read_b128 v[228:231], v145 offset:55296
	ds_read_b128 v[232:235], v145 offset:56320
	global_load_lds_dwordx4 v[140:141], off
	s_add_i32 m0, s46, 0x2000
	s_add_u32 s46, s50, 0xb0080
	v_lshl_add_u64 v[140:141], v[190:191], 0, s[8:9]
	s_addc_u32 s47, s51, 0
	s_add_i32 s50, s71, s55
	global_load_lds_dwordx4 v[140:141], off
	v_lshl_add_u64 v[140:141], s[46:47], 0, v[0:1]
	s_mov_b32 m0, s50
	s_nop 0
	global_load_lds_dwordx4 v[140:141], off
	v_lshl_add_u64 v[140:141], s[46:47], 0, v[130:131]
	s_add_i32 m0, s50, 0x2000
	s_nop 0
	global_load_lds_dwordx4 v[140:141], off
	v_lshl_add_u64 v[140:141], v[236:237], 0, s[8:9]
	s_mov_b32 m0, s60
	s_nop 0
	global_load_lds_dwordx4 v[140:141], off
	v_lshl_add_u64 v[140:141], v[238:239], 0, s[8:9]
	s_mov_b32 m0, s61
	s_nop 0
	global_load_lds_dwordx4 v[140:141], off
	s_waitcnt vmcnt(8)
	s_waitcnt lgkmcnt(0)
	s_barrier
	s_setprio 1
	s_waitcnt lgkmcnt(0)
	v_mfma_f32_16x16x32_bf16 v[62:65], v[146:149], v[200:203], v[62:65]
	v_mfma_f32_16x16x32_bf16 v[58:61], v[154:157], v[200:203], v[58:61]
	v_mfma_f32_16x16x32_bf16 v[50:53], v[146:149], v[212:215], v[50:53]
	v_mfma_f32_16x16x32_bf16 v[42:45], v[154:157], v[212:215], v[42:45]
	v_mfma_f32_16x16x32_bf16 v[34:37], v[146:149], v[220:223], v[34:37]
	v_mfma_f32_16x16x32_bf16 v[26:29], v[154:157], v[220:223], v[26:29]
	v_mfma_f32_16x16x32_bf16 v[18:21], v[146:149], v[228:231], v[18:21]
	v_mfma_f32_16x16x32_bf16 v[10:13], v[154:157], v[228:231], v[10:13]
	v_mfma_f32_16x16x32_bf16 v[62:65], v[150:153], v[208:211], v[62:65]
	v_mfma_f32_16x16x32_bf16 v[58:61], v[158:161], v[208:211], v[58:61]
	v_mfma_f32_16x16x32_bf16 v[50:53], v[150:153], v[216:219], v[50:53]
	v_mfma_f32_16x16x32_bf16 v[42:45], v[158:161], v[216:219], v[42:45]
	v_mfma_f32_16x16x32_bf16 v[34:37], v[150:153], v[224:227], v[34:37]
	v_mfma_f32_16x16x32_bf16 v[26:29], v[158:161], v[224:227], v[26:29]
	v_mfma_f32_16x16x32_bf16 v[18:21], v[150:153], v[232:235], v[18:21]
	v_mfma_f32_16x16x32_bf16 v[10:13], v[158:161], v[232:235], v[10:13]
	s_setprio 0
	s_setprio 1
	v_mfma_f32_16x16x32_bf16 v[54:57], v[174:177], v[200:203], v[54:57]
	v_mfma_f32_16x16x32_bf16 v[46:49], v[182:185], v[200:203], v[46:49]
	v_mfma_f32_16x16x32_bf16 v[38:41], v[174:177], v[212:215], v[38:41]
	v_mfma_f32_16x16x32_bf16 v[30:33], v[182:185], v[212:215], v[30:33]
	v_mfma_f32_16x16x32_bf16 v[22:25], v[174:177], v[220:223], v[22:25]
	v_mfma_f32_16x16x32_bf16 v[14:17], v[182:185], v[220:223], v[14:17]
	v_mfma_f32_16x16x32_bf16 v[6:9], v[174:177], v[228:231], v[6:9]
	v_mfma_f32_16x16x32_bf16 v[2:5], v[182:185], v[228:231], v[2:5]
	v_mfma_f32_16x16x32_bf16 v[54:57], v[178:181], v[208:211], v[54:57]
	v_mfma_f32_16x16x32_bf16 v[46:49], v[186:189], v[208:211], v[46:49]
	v_mfma_f32_16x16x32_bf16 v[38:41], v[178:181], v[216:219], v[38:41]
	v_mfma_f32_16x16x32_bf16 v[30:33], v[186:189], v[216:219], v[30:33]
	s_barrier
	v_mfma_f32_16x16x32_bf16 v[22:25], v[178:181], v[224:227], v[22:25]
	v_mfma_f32_16x16x32_bf16 v[14:17], v[186:189], v[224:227], v[14:17]
	v_mfma_f32_16x16x32_bf16 v[6:9], v[178:181], v[232:235], v[6:9]
	v_mfma_f32_16x16x32_bf16 v[2:5], v[186:189], v[232:235], v[2:5]
	s_setprio 0
	s_nop 0
	s_add_i32 s73, s73, 2
	s_add_u32 s16, s16, 0x100
	s_addc_u32 s17, s17, 0
	s_cmp_gt_u32 s73, 41
	s_mov_b64 s[46:47], s[48:49]
	s_cbranch_scc0 .LBB0_656
	s_and_b64 vcc, exec, s[42:43]
	s_cbranch_vccz .LBB0_659
	s_barrier
